# on the 4-segment + LDS-address version: m0-hazard nops replaced by following scalar instructions, P8 unit order permuted so each XCD works on a compact 4x8 tile patch
# baseline (speedup 1.0000x reference)
.LBB0_6:
	s_mov_b32 s27, 11
	s_add_u32 s12, s24, 0x8a19c00
	s_addc_u32 s13, s25, 0
	s_add_u32 s34, s24, 0x3400000
	s_addc_u32 s35, s25, 0
	s_add_u32 s54, s24, 0x4f00000
	s_addc_u32 s55, s25, 0
	s_add_u32 s96, s24, 0x152b7000
	s_addc_u32 s97, s25, 0
	s_cmpk_lg_i32 s52, 0x100
	s_cselect_b64 s[4:5], -1, 0
	v_writelane_b32 v250, s4, 2
	s_ashr_i32 s36, s68, 3
	s_load_dwordx16 s[80:95], s[0:1], 0x80
	v_writelane_b32 v250, s5, 3
	s_lshl_b32 s4, s68, 5
	s_and_b32 s4, s4, 0xe0
	s_add_i32 s39, s4, s36
	s_cmpk_eq_i32 s52, 0x100
	s_cselect_b64 s[4:5], -1, 0
	v_writelane_b32 v250, s4, 4
	v_mbcnt_lo_u32_b32 v2, -1, 0
	v_mbcnt_hi_u32_b32 v163, -1, v2
	v_writelane_b32 v250, s5, 5
	s_and_b64 s[4:5], s[4:5], exec
	s_cselect_b32 s33, s39, s68
	s_movk_i32 s4, 0x300
	s_cselect_b32 s46, s4, 0x339
	s_cmpk_lt_i32 s33, 0x1b0
	s_cselect_b64 s[4:5], -1, 0
	v_writelane_b32 v250, s4, 6
	s_cmpk_lt_i32 s33, 0x100
	v_mov_b32_e32 v158, 0x358637bd
	v_writelane_b32 v250, s5, 7
	s_cselect_b64 s[4:5], -1, 0
	s_and_b32 s15, s33, 7
	s_bfe_u32 s6, s33, 0x50003
	s_add_u32 s7, s24, 0x13a19c00
	s_addc_u32 s8, s25, 0
	s_lshl_b32 s31, s6, 9
	s_add_u32 s14, s7, s31
	v_writelane_b32 v250, s6, 8
	s_mul_i32 s6, s15, 0x2c0000
	s_addc_u32 s16, s8, 0
	s_add_u32 s6, s34, s6
	v_writelane_b32 v250, s7, 9
	s_addc_u32 s7, s35, 0
	s_add_u32 s17, s6, s31
	s_addc_u32 s18, s7, 0
	s_ashr_i32 s6, s33, 31
	s_lshr_b32 s6, s6, 27
	s_add_i32 s6, s33, s6
	s_ashr_i32 s7, s6, 5
	s_andn2_b32 s6, s6, 31
	s_sub_i32 s6, s33, s6
	v_writelane_b32 v250, s8, 10
	s_ashr_i32 s8, s6, 31
	s_lshr_b32 s8, s8, 30
	s_lshl_b32 s7, s7, 2
	s_add_i32 s9, s6, s8
	s_add_i32 s6, s6, s7
	s_and_b32 s7, s9, -4
	s_sub_i32 s6, s6, s7
	s_ashr_i32 s8, s9, 2
	s_ashr_i32 s7, s6, 31
	s_mul_i32 s11, s6, 0x580000
	s_mul_hi_i32 s9, s6, 0x580000
	s_add_u32 s19, s12, s11
	v_writelane_b32 v250, s12, 11
	s_addc_u32 s29, s13, s9
	s_ashr_i32 s9, s8, 31
	s_mul_i32 s12, s8, 0x2c0000
	v_writelane_b32 v250, s13, 12
	s_mul_hi_i32 s11, s8, 0x2c0000
	s_add_u32 s57, s34, s12
	v_writelane_b32 v250, s34, 13
	s_addc_u32 s30, s35, s11
	s_lshl_b32 s11, s68, 9
	s_lshl_b32 s28, s52, 9
	s_add_u32 vcc_lo, s24, 0x8a17000
	s_addc_u32 vcc_hi, s25, 0
	s_add_u32 s48, s24, 0x6917000
	s_addc_u32 s49, s25, 0
	s_add_u32 s50, s24, 0x800000
	s_addc_u32 s51, s25, 0
	v_writelane_b32 v250, s35, 14
	s_cmpk_lt_i32 s33, 0x5ac
	v_writelane_b32 v250, s11, 15
	s_cselect_b64 s[12:13], -1, 0
	v_writelane_b32 v250, s12, 16
	s_and_b32 s34, s33, 7
	s_lshl_b32 s34, s34, 5
	s_lshr_b32 s35, s33, 3
	s_or_b32 s34, s34, s35
	s_mul_hi_i32 s11, s34, 0x2e8ba2e9
	v_mov_b32_e32 v202, 0x260
	v_writelane_b32 v250, s13, 17
	s_lshr_b32 s12, s11, 31
	s_ashr_i32 s11, s11, 5
	s_add_i32 s11, s11, s12
	s_mul_i32 s13, s11, 0xffffff50
	s_lshl_b32 s12, s11, 2
	s_sub_i32 s11, 33, s12
	s_add_i32 s13, s13, s34
	s_min_u32 s11, s11, 4
	s_add_i32 s12, s13, s12
	s_cmpk_lt_i32 s68, 0x108
	s_cselect_b64 s[34:35], -1, 0
	s_add_u32 s70, s24, 0x5017000
	s_addc_u32 s71, s25, 0
	v_writelane_b32 v250, s34, 18
	s_cmpk_lt_i32 s33, 0x140
	v_cvt_f32_ubyte0_e32 v1, s11
	v_writelane_b32 v250, s35, 19
	s_cselect_b64 s[34:35], -1, 0
	v_writelane_b32 v250, s34, 20
	v_rcp_iflag_f32_e32 v1, v1
	v_mov_b32_e32 v160, 1.0
	v_writelane_b32 v250, s35, 21
	s_add_u32 s34, s24, 0x7017000
	s_addc_u32 s35, s25, 0
	s_add_u32 s37, s34, s31
	v_writelane_b32 v250, s34, 22
	s_addc_u32 s38, s35, 0
	s_lshl_b32 s34, s15, 20
	s_add_u32 s34, s24, s34
	v_writelane_b32 v250, s35, 23
	s_addc_u32 s35, s25, 0
	s_add_u32 s41, s34, s31
	s_addc_u32 s43, s35, 0
	s_lshl_b64 s[34:35], s[6:7], 20
	s_add_u32 s40, s70, s34
	s_addc_u32 s42, s71, s35
	s_lshl_b64 s[34:35], s[8:9], 20
	s_add_u32 s44, s24, s34
	s_addc_u32 s45, s25, s35
	s_add_u32 s72, s24, 0xbb97000
	s_addc_u32 s73, s25, 0
	s_add_u32 s34, s24, 0x172f7000
	s_addc_u32 s35, s25, 0
	v_writelane_b32 v250, s34, 24
	v_mul_f32_e32 v1, 0x4f7ffffe, v1
	v_cvt_u32_f32_e32 v1, v1
	v_writelane_b32 v250, s35, 25
	s_add_u32 s34, s24, 0x4f90000
	s_addc_u32 s35, s25, 0
	s_lshl_b32 s47, s68, 3
	s_lshl_b32 s56, s52, 3
	s_add_u32 s64, s22, 0x4000000
	v_writelane_b32 v250, s34, 26
	s_addc_u32 s65, s23, 0
	v_mov_b32_e32 v203, 1
	v_writelane_b32 v250, s35, 27
	s_add_u32 s34, s24, 0xab17000
	s_addc_u32 s35, s25, 0
	v_writelane_b32 v250, s34, 28
	v_mov_b32_e32 v204, 0x7fe
	v_mov_b32_e32 v205, 0x520d000
	v_writelane_b32 v250, s35, 29
	s_add_u32 s34, s22, 0x52b9000
	s_addc_u32 s35, s23, 0
	v_writelane_b32 v250, s34, 30
	v_mov_b32_e32 v206, 0x5553000
	v_mov_b32_e32 v207, 0x1800
	v_writelane_b32 v250, s35, 31
	s_add_u32 s34, s22, 0x4900000
	s_addc_u32 s35, s23, 0
	v_writelane_b32 v250, s34, 32
	s_cmpk_lt_i32 s68, 0x300
	v_mov_b32_e32 v208, 0xfffff800
	v_writelane_b32 v250, s35, 33
	s_cselect_b64 s[34:35], -1, 0
	s_add_u32 s66, s24, 0x111b7000
	s_addc_u32 s67, s25, 0
	s_add_u32 s58, s24, 0xf137000
	v_writelane_b32 v250, s34, 34
	s_addc_u32 s59, s25, 0
	s_add_u32 s7, s22, 0x5339000
	v_writelane_b32 v250, s35, 35
	v_writelane_b32 v250, s7, 36
	s_addc_u32 s7, s23, 0
	v_writelane_b32 v250, s7, 37
	s_add_u32 s7, s22, 0x5100000
	v_writelane_b32 v250, s7, 38
	s_addc_u32 s7, s23, 0
	v_writelane_b32 v250, s7, 39
	s_add_u32 s7, s24, 0x5012200
	v_writelane_b32 v250, s7, 40
	s_addc_u32 s7, s25, 0
	s_add_u32 s34, s24, 0x16af7000
	s_addc_u32 s35, s25, 0
	s_cmp_eq_u32 s68, 0
	v_writelane_b32 v250, s7, 41
	s_cselect_b64 s[74:75], -1, 0
	v_writelane_b32 v250, s74, 42
	v_mov_b32_e32 v162, 0x3a27c5ac
	v_mov_b32_e32 v214, 0x80
	v_writelane_b32 v250, s75, 43
	s_add_u32 s74, s24, 0x5012000
	s_addc_u32 s75, s25, 0
	s_add_i32 s7, s39, 0x300
	v_writelane_b32 v250, s74, 44
	s_cmp_lt_i32 s39, 57
	v_mov_b32_e32 v215, 0x1000000
	v_writelane_b32 v250, s75, 45
	s_cselect_b64 s[74:75], -1, 0
	v_writelane_b32 v250, s74, 46
	s_cmpk_lt_i32 s39, 0xffb5
	v_mov_b64_e32 v[164:165], 0x16af7000
	v_writelane_b32 v250, s75, 47
	s_cselect_b64 s[74:75], -1, 0
	s_add_i32 s9, s39, 0x4b
	v_writelane_b32 v250, s74, 48
	s_and_b32 s31, s9, 3
	v_mov_b32_e32 v216, 0xf149f2ca
	v_writelane_b32 v250, s75, 49
	s_lshr_b32 s74, s9, 2
	s_lshl_b32 s9, s31, 20
	v_writelane_b32 v250, s39, 50
	s_add_u32 s9, s70, s9
	v_writelane_b32 v250, s31, 51
	s_addc_u32 s31, s71, 0
	s_add_u32 s76, s9, 0x800000
	s_mul_hi_i32 s9, s7, 0x30c30c31
	s_addc_u32 s77, s31, 0
	s_lshr_b32 s31, s9, 31
	s_ashr_i32 s9, s9, 4
	s_add_i32 s9, s9, s31
	v_writelane_b32 v250, s76, 52
	s_mul_i32 s31, s9, 0xffffffac
	s_lshl_b32 s9, s9, 2
	s_add_i32 s36, s36, -1
	v_writelane_b32 v250, s77, 53
	s_add_i32 s31, s31, s7
	s_sub_i32 s7, 33, s9
	s_and_b32 s36, s36, 3
	s_min_u32 s7, s7, 4
	s_add_i32 s9, s31, s9
	v_writelane_b32 v250, s36, 54
	s_lshl_b32 s36, s36, 20
	s_add_u32 s36, s70, s36
	s_addc_u32 s39, s71, 0
	s_add_u32 s76, s36, 0x800000
	s_addc_u32 s77, s39, 0
	v_writelane_b32 v250, s76, 55
	v_mov_b32_e32 v217, -4
	v_mov_b32_e32 v218, 0x200f
	v_writelane_b32 v250, s77, 56
	s_add_u32 s76, s22, 0x4100000
	s_addc_u32 s77, s23, 0
	v_writelane_b32 v250, s76, 57
	v_mov_b32_e32 v219, 0x41b17218
	v_mov_b32_e32 v222, 0xfff3a000
	v_writelane_b32 v250, s77, 58
	s_add_u32 s76, s22, 0x5239000
	s_addc_u32 s77, s23, 0
	v_writelane_b32 v250, s76, 59
	s_ashr_i32 s69, s68, 31
	s_ashr_i32 s53, s52, 31
	v_writelane_b32 v250, s77, 60
	s_lshl_b64 s[76:77], s[68:69], 9
	v_writelane_b32 v250, s76, 61
	v_mov_b32_e32 v223, 6
	s_movk_i32 s69, 0x5ff
	v_writelane_b32 v250, s77, 62
	s_lshl_b64 s[76:77], s[52:53], 9
	s_add_u32 s78, s24, 0x4a00000
	v_writelane_b32 v250, s76, 63
	s_addc_u32 s79, s25, 0
	s_nop 0
	v_writelane_b32 v251, s77, 0
	s_add_u32 s76, s24, 0x5012100
	s_addc_u32 s77, s25, 0
	v_writelane_b32 v251, s76, 1
	s_waitcnt lgkmcnt(0)
	s_add_u32 s60, s82, 0x3000
	v_writelane_b32 v251, s77, 2
	v_writelane_b32 v251, s80, 3
	s_addc_u32 s61, s83, 0
	s_cmp_lt_i32 s33, s46
	v_writelane_b32 v251, s81, 4
	v_writelane_b32 v251, s82, 5
	v_writelane_b32 v251, s83, 6
	v_writelane_b32 v251, s84, 7
	v_writelane_b32 v251, s85, 8
	v_writelane_b32 v251, s86, 9
	v_writelane_b32 v251, s87, 10
	v_writelane_b32 v251, s88, 11
	v_writelane_b32 v251, s89, 12
	v_writelane_b32 v251, s90, 13
	v_writelane_b32 v251, s91, 14
	v_writelane_b32 v251, s92, 15
	v_writelane_b32 v251, s93, 16
	v_writelane_b32 v251, s94, 17
	v_writelane_b32 v251, s95, 18
	v_writelane_b32 v251, s60, 19
	s_mov_b64 s[90:91], s[54:55]
	s_mov_b32 s88, s52
	v_writelane_b32 v251, s61, 20
	v_writelane_b32 v251, s46, 21
	s_cselect_b64 s[60:61], -1, 0
	v_writelane_b32 v251, s60, 22
	s_cmpk_lt_i32 s33, 0x2b5
	s_movk_i32 s93, 0x210
	v_writelane_b32 v251, s61, 23
	s_cselect_b64 s[60:61], -1, 0
	s_add_i32 s36, s33, 0xfffffd4b
	v_writelane_b32 v251, s60, 24
	s_and_b32 s39, s36, 3
	s_mov_b64 s[94:95], 0x80
	v_writelane_b32 v251, s61, 25
	s_lshr_b32 s60, s36, 2
	s_lshl_b32 s36, s39, 20
	s_add_u32 s36, s70, s36
	v_writelane_b32 v251, s39, 26
	s_addc_u32 s39, s71, 0
	s_add_u32 s62, s36, 0x800000
	s_mul_hi_i32 s36, s33, 0x30c30c31
	s_addc_u32 s63, s39, 0
	s_lshr_b32 s39, s36, 31
	s_ashr_i32 s36, s36, 4
	s_add_i32 s36, s36, s39
	s_mul_i32 s39, s36, 0xffffffac
	s_lshl_b32 s36, s36, 2
	s_add_i32 s39, s39, s33
	s_sub_i32 s33, 33, s36
	v_writelane_b32 v251, s62, 27
	s_min_u32 s33, s33, 4
	s_add_i32 s36, s39, s36
	v_writelane_b32 v251, s63, 28
	s_add_u32 s62, s24, 0x4a80000
	s_addc_u32 s63, s25, 0
	v_writelane_b32 v251, s62, 29
	s_cmp_lt_i32 s68, 12
	s_mov_b32 s92, 0x3e027906
	v_writelane_b32 v251, s63, 30
	s_cselect_b64 s[62:63], -1, 0
	v_writelane_b32 v251, s62, 31
	s_cmpk_lt_i32 s68, 0x180
	s_nop 0
	v_writelane_b32 v251, s63, 32
	s_cselect_b64 s[62:63], -1, 0
	v_writelane_b32 v251, s62, 33
	s_nop 1
	v_writelane_b32 v251, s63, 34
	s_add_u32 s62, s24, 0x4a00100
	s_addc_u32 s63, s25, 0
	v_writelane_b32 v251, s62, 35
	s_nop 1
	v_writelane_b32 v251, s63, 36
	s_add_u32 s62, s24, 0x4a00080
	s_addc_u32 s63, s25, 0
	v_writelane_b32 v251, s62, 37
	s_cmp_lt_i32 s27, 0
	s_nop 0
	v_writelane_b32 v251, s63, 38
	s_cselect_b64 s[62:63], -1, 0
	v_writelane_b32 v251, s62, 39
	s_nop 1
	v_writelane_b32 v251, s63, 40
	s_add_u32 s62, s24, 0x5013200
	s_addc_u32 s63, s25, 0
	v_writelane_b32 v251, s62, 41
	s_nop 1
	v_writelane_b32 v251, s63, 42
	s_add_u32 s62, s24, 0x5013400
	s_addc_u32 s63, s25, 0
	v_writelane_b32 v251, s62, 43
	s_nop 1
	v_writelane_b32 v251, s63, 44
	s_add_u32 s62, s24, 0x5013500
	s_addc_u32 s63, s25, 0
	v_writelane_b32 v251, s62, 45
	s_nop 1
	v_writelane_b32 v251, s63, 46
	s_add_u32 s62, s24, 0x5013600
	s_addc_u32 s63, s25, 0
	v_writelane_b32 v251, s62, 47
	s_nop 1
	v_writelane_b32 v251, s63, 48
	s_add_u32 s62, s24, 0x5013700
	s_addc_u32 s63, s25, 0
	v_writelane_b32 v251, s62, 49
	s_nop 1
	v_writelane_b32 v251, s63, 50
	s_add_u32 s62, s24, 0x5013800
	s_addc_u32 s63, s25, 0
	v_writelane_b32 v251, s62, 51
	s_nop 1
	v_writelane_b32 v251, s63, 52
	s_add_u32 s62, s24, 0x5013900
	s_addc_u32 s63, s25, 0
	v_writelane_b32 v251, s62, 53
	s_nop 1
	v_writelane_b32 v251, s63, 54
	s_add_u32 s62, s24, 0x5013a00
	s_addc_u32 s63, s25, 0
	v_writelane_b32 v251, s62, 55
	s_nop 1
	v_writelane_b32 v251, s63, 56
	s_add_u32 s62, s24, 0x5013b00
	s_addc_u32 s63, s25, 0
	v_writelane_b32 v251, s62, 57
	s_nop 1
	v_writelane_b32 v251, s63, 58
	s_add_u32 s62, s24, 0x5013c00
	s_addc_u32 s63, s25, 0
	v_writelane_b32 v251, s62, 59
	s_nop 1
	v_writelane_b32 v251, s63, 60
	s_add_u32 s62, s24, 0x5013d00
	s_addc_u32 s63, s25, 0
	v_writelane_b32 v251, s62, 61
	s_nop 1
	v_writelane_b32 v251, s63, 62
	s_add_u32 s62, s24, 0x5013e00
	s_addc_u32 s63, s25, 0
	v_writelane_b32 v251, s62, 63
	s_nop 1
	v_writelane_b32 v252, s63, 0
	s_add_u32 s62, s24, 0x5013f00
	s_addc_u32 s63, s25, 0
	v_writelane_b32 v252, s62, 1
	s_nop 1
	v_writelane_b32 v252, s63, 2
	s_add_u32 s62, s24, 0x5014000
	s_addc_u32 s63, s25, 0
	v_writelane_b32 v252, s62, 3
	s_nop 1
	v_writelane_b32 v252, s63, 4
	s_add_u32 s62, s24, 0x5014100
	s_addc_u32 s63, s25, 0
	v_writelane_b32 v252, s62, 5
	s_nop 1
	v_writelane_b32 v252, s63, 6
	s_add_u32 s62, s24, 0x5014200
	s_addc_u32 s63, s25, 0
	v_writelane_b32 v252, s62, 7
	s_nop 1
	v_writelane_b32 v252, s63, 8
	s_add_u32 s62, s24, 0x5014300
	s_addc_u32 s63, s25, 0
	v_writelane_b32 v252, s62, 9
	s_cmp_eq_u32 s10, 15
	s_nop 0
	v_writelane_b32 v252, s63, 10
	s_cselect_b64 s[62:63], -1, 0
	v_writelane_b32 v252, s62, 11
	s_cmp_eq_u32 s10, 14
	s_nop 0
	v_writelane_b32 v252, s63, 12
	s_cselect_b64 s[62:63], -1, 0
	v_writelane_b32 v252, s62, 13
	s_cmp_eq_u32 s10, 13
	s_nop 0
	v_writelane_b32 v252, s63, 14
	s_cselect_b64 s[62:63], -1, 0
	v_writelane_b32 v252, s62, 15
	s_cmp_eq_u32 s10, 12
	s_nop 0
	v_writelane_b32 v252, s63, 16
	s_cselect_b64 s[62:63], -1, 0
	v_writelane_b32 v252, s62, 17
	s_cmp_eq_u32 s10, 11
	s_nop 0
	v_writelane_b32 v252, s63, 18
	s_cselect_b64 s[62:63], -1, 0
	v_writelane_b32 v252, s62, 19
	s_cmp_eq_u32 s10, 10
	s_nop 0
	v_writelane_b32 v252, s63, 20
	s_cselect_b64 s[62:63], -1, 0
	v_writelane_b32 v252, s62, 21
	s_cmp_eq_u32 s10, 9
	s_nop 0
	v_writelane_b32 v252, s63, 22
	s_cselect_b64 s[62:63], -1, 0
	v_writelane_b32 v252, s62, 23
	s_cmp_eq_u32 s10, 8
	s_nop 0
	v_writelane_b32 v252, s63, 24
	s_cselect_b64 s[62:63], -1, 0
	v_writelane_b32 v252, s62, 25
	s_cmp_eq_u32 s10, 7
	s_nop 0
	v_writelane_b32 v252, s63, 26
	s_cselect_b64 s[62:63], -1, 0
	v_writelane_b32 v252, s62, 27
	s_cmp_eq_u32 s10, 6
	s_nop 0
	v_writelane_b32 v252, s63, 28
	s_cselect_b64 s[62:63], -1, 0
	v_writelane_b32 v252, s62, 29
	s_cmp_eq_u32 s10, 5
	s_nop 0
	v_writelane_b32 v252, s63, 30
	s_cselect_b64 s[62:63], -1, 0
	v_writelane_b32 v252, s62, 31
	s_cmp_eq_u32 s10, 4
	s_nop 0
	v_writelane_b32 v252, s63, 32
	s_cselect_b64 s[62:63], -1, 0
	v_writelane_b32 v252, s62, 33
	s_cmp_eq_u32 s10, 3
	s_nop 0
	v_writelane_b32 v252, s63, 34
	s_cselect_b64 s[62:63], -1, 0
	v_writelane_b32 v252, s62, 35
	s_cmp_eq_u32 s10, 2
	s_nop 0
	v_writelane_b32 v252, s63, 36
	s_cselect_b64 s[62:63], -1, 0
	v_writelane_b32 v252, s62, 37
	s_cmp_eq_u32 s10, 1
	s_nop 0
	v_writelane_b32 v252, s63, 38
	s_cselect_b64 s[62:63], -1, 0
	v_writelane_b32 v252, s62, 39
	s_cmp_eq_u32 s10, 0
	s_nop 0
	v_writelane_b32 v252, s63, 40
	s_cselect_b64 s[62:63], -1, 0
	s_lshl_b32 s10, s10, 8
	s_add_u32 s2, s2, s10
	v_writelane_b32 v252, s62, 41
	s_addc_u32 s3, s3, 0
	s_nop 0
	v_writelane_b32 v252, s63, 42
	s_add_u32 s62, s2, 0x1400
	s_addc_u32 s63, s3, 0
	v_writelane_b32 v252, s62, 43
	s_add_u32 s2, s2, 0x2400
	s_addc_u32 s3, s3, 0
	v_writelane_b32 v252, s63, 44
	v_writelane_b32 v252, s2, 45
	s_nop 1
	v_writelane_b32 v252, s3, 46
	s_add_u32 s2, s24, 0x5016400
	s_addc_u32 s3, s25, 0
	v_writelane_b32 v252, s2, 47
	s_nop 1
	v_writelane_b32 v252, s3, 48
	s_add_u32 s2, s24, 0x5016500
	s_addc_u32 s3, s25, 0
	v_writelane_b32 v252, s2, 49
	s_nop 1
	v_writelane_b32 v252, s3, 50
	s_and_b64 s[2:3], s[4:5], exec
	s_cselect_b32 s2, s8, s15
	v_writelane_b32 v252, s2, 51
	s_cselect_b32 s6, s6, 32
	v_writelane_b32 v252, s6, 52
	s_cselect_b32 s6, 0x58, 4
	s_cselect_b32 s2, s57, s17
	v_writelane_b32 v252, s6, 53
	s_cselect_b32 s6, 0, 2
	s_cselect_b32 s3, s30, s18
	s_cselect_b32 s5, s29, s16
	s_cselect_b32 s4, s19, s14
	s_cselect_b32 s15, s45, s43
	s_cselect_b32 s14, s44, s41
	s_cselect_b32 s17, s42, s38
	s_cselect_b32 s16, s40, s37
	v_writelane_b32 v252, s6, 54
	s_cselect_b32 s6, 32, 4
	s_add_u32 s18, s2, 0x160000
	v_writelane_b32 v252, s6, 55
	s_addc_u32 s19, s3, 0
	v_writelane_b32 v252, s18, 56
	s_mov_b32 s37, 0
	s_mov_b32 s75, s37
	v_writelane_b32 v252, s19, 57
	s_add_u32 s18, s4, 0x2c0000
	v_writelane_b32 v252, s4, 58
	s_addc_u32 s19, s5, 0
	s_mov_b32 s61, s37
	v_writelane_b32 v252, s5, 59
	v_writelane_b32 v252, s18, 60
	s_add_u32 s4, s2, 0x160080
	s_mov_b32 s30, 0x3f07dc22
	v_writelane_b32 v252, s19, 61
	v_writelane_b32 v252, s2, 62
	s_addc_u32 s5, s3, 0
	v_writelane_b32 v253, s4, 0
	v_writelane_b32 v252, s3, 63
	s_add_u32 s2, s14, 0x80000
	v_writelane_b32 v253, s5, 1
	s_addc_u32 s3, s15, 0
	v_writelane_b32 v253, s2, 2
	s_nop 1
	v_writelane_b32 v253, s3, 3
	s_add_u32 s2, s16, 0x80000
	v_writelane_b32 v253, s16, 4
	s_addc_u32 s3, s17, 0
	s_nop 0
	v_writelane_b32 v253, s17, 5
	v_writelane_b32 v253, s2, 6
	s_nop 1
	v_writelane_b32 v253, s3, 7
	s_add_u32 s2, s14, 0x80080
	v_writelane_b32 v253, s14, 8
	s_addc_u32 s3, s15, 0
	s_nop 0
	v_writelane_b32 v253, s15, 9
	v_writelane_b32 v253, s2, 10
	s_nop 1
	v_writelane_b32 v253, s3, 11
	s_sub_i32 s2, 0, s11
	v_readfirstlane_b32 s3, v1
	s_mul_i32 s2, s2, s3
	s_mul_hi_u32 s2, s3, s2
	s_add_i32 s3, s3, s2
	s_abs_i32 s2, s13
	s_mul_hi_u32 s3, s2, s3
	s_mul_i32 s4, s3, s11
	s_sub_i32 s2, s2, s4
	s_ashr_i32 s4, s13, 31
	s_add_i32 s5, s3, 1
	s_sub_i32 s6, s2, s11
	s_cmp_ge_u32 s2, s11
	s_cselect_b32 s3, s5, s3
	s_cselect_b32 s2, s6, s2
	s_add_i32 s5, s3, 1
	s_cmp_ge_u32 s2, s11
	s_cselect_b32 s2, s5, s3
	s_xor_b32 s2, s2, s4
	s_sub_i32 s4, s2, s4
	s_mul_i32 s11, s11, s4
	s_sub_i32 s10, s12, s11
	s_mov_b32 s2, s10
	s_ashr_i32 s11, s10, 31
	v_writelane_b32 v253, s2, 12
	v_cvt_f32_ubyte0_e32 v1, s7
	v_rcp_iflag_f32_e32 v1, v1
	v_writelane_b32 v253, s3, 13
	s_lshl_b64 s[2:3], s[10:11], 20
	s_add_u32 s10, s48, s2
	s_mov_b32 s2, s4
	s_addc_u32 s11, s49, s3
	s_ashr_i32 s5, s4, 31
	v_writelane_b32 v253, s2, 14
	v_mul_f32_e32 v1, 0x4f7ffffe, v1
	v_cvt_u32_f32_e32 v1, v1
	v_writelane_b32 v253, s3, 15
	s_lshl_b64 s[2:3], s[4:5], 20
	s_add_u32 s2, s50, s2
	v_writelane_b32 v253, s50, 16
	s_addc_u32 s3, s51, s3
	s_add_u32 s4, s2, 0x80000
	v_writelane_b32 v253, s51, 17
	s_addc_u32 s5, s3, 0
	v_writelane_b32 v253, s4, 18
	s_nop 1
	v_writelane_b32 v253, s5, 19
	s_add_u32 s4, s10, 0x80000
	v_writelane_b32 v253, s10, 20
	s_addc_u32 s5, s11, 0
	s_nop 0
	v_writelane_b32 v253, s11, 21
	v_writelane_b32 v253, s4, 22
	s_nop 1
	v_writelane_b32 v253, s5, 23
	s_add_u32 s4, s2, 0x80080
	v_writelane_b32 v253, s2, 24
	s_addc_u32 s5, s3, 0
	s_nop 0
	v_writelane_b32 v253, s3, 25
	s_sub_i32 s2, 0, s7
	v_readfirstlane_b32 s3, v1
	s_mul_i32 s2, s2, s3
	s_mul_hi_u32 s2, s3, s2
	s_add_i32 s3, s3, s2
	s_abs_i32 s2, s31
	v_writelane_b32 v253, s4, 26
	s_mul_hi_u32 s3, s2, s3
	v_cvt_f32_ubyte0_e32 v1, s33
	v_writelane_b32 v253, s5, 27
	s_mul_i32 s4, s3, s7
	s_sub_i32 s2, s2, s4
	s_ashr_i32 s4, s31, 31
	s_add_i32 s5, s3, 1
	s_sub_i32 s6, s2, s7
	s_cmp_ge_u32 s2, s7
	s_cselect_b32 s3, s5, s3
	s_cselect_b32 s2, s6, s2
	s_add_i32 s5, s3, 1
	s_cmp_ge_u32 s2, s7
	s_cselect_b32 s2, s5, s3
	s_xor_b32 s2, s2, s4
	s_sub_i32 s2, s2, s4
	s_mul_i32 s7, s7, s2
	v_rcp_iflag_f32_e32 v1, v1
	s_sub_i32 s4, s9, s7
	s_add_i32 s3, s2, 4
	s_cmp_lt_i32 s2, 8
	s_cselect_b32 s6, s2, s3
	s_mov_b32 s2, s4
	s_ashr_i32 s5, s4, 31
	v_writelane_b32 v253, s2, 28
	v_mul_f32_e32 v1, 0x4f7ffffe, v1
	v_cvt_u32_f32_e32 v1, v1
	v_writelane_b32 v253, s3, 29
	s_lshl_b64 s[2:3], s[4:5], 20
	s_add_u32 s2, s48, s2
	s_addc_u32 s3, s49, s3
	v_writelane_b32 v253, s2, 30
	s_ashr_i32 s7, s6, 31
	s_mov_b32 s31, 0x3e6d3388
	v_writelane_b32 v253, s3, 31
	s_sub_i32 s2, 0, s33
	v_readfirstlane_b32 s3, v1
	s_mul_i32 s2, s2, s3
	s_mul_hi_u32 s2, s3, s2
	s_add_i32 s3, s3, s2
	s_abs_i32 s2, s39
	s_mul_hi_u32 s3, s2, s3
	s_mul_i32 s4, s3, s33
	s_sub_i32 s2, s2, s4
	v_writelane_b32 v253, s6, 32
	s_ashr_i32 s4, s39, 31
	s_add_i32 s5, s3, 1
	v_writelane_b32 v253, s7, 33
	s_sub_i32 s6, s2, s33
	s_cmp_ge_u32 s2, s33
	s_cselect_b32 s3, s5, s3
	s_cselect_b32 s2, s6, s2
	s_add_i32 s5, s3, 1
	s_cmp_ge_u32 s2, s33
	s_cselect_b32 s2, s5, s3
	s_xor_b32 s2, s2, s4
	s_sub_i32 s2, s2, s4
	s_mul_i32 s33, s33, s2
	s_sub_i32 s4, s36, s33
	s_add_i32 s3, s2, 4
	s_cmp_lt_i32 s2, 8
	s_cselect_b32 s6, s2, s3
	s_mov_b32 s2, s4
	s_ashr_i32 s5, s4, 31
	v_writelane_b32 v253, s2, 34
	v_lshrrev_b32_e32 v1, 20, v0
	v_lshrrev_b32_e32 v0, 10, v0
	v_writelane_b32 v253, s3, 35
	s_lshl_b64 s[2:3], s[4:5], 20
	s_add_u32 s2, s48, s2
	v_writelane_b32 v253, s48, 36
	s_addc_u32 s3, s49, s3
	s_ashr_i32 s7, s6, 31
	v_writelane_b32 v253, s49, 37
	v_writelane_b32 v253, s2, 38
	v_or_b32_e32 v0, v0, v1
	v_mov_b32_e32 v1, 0
	v_writelane_b32 v253, s3, 39
	v_writelane_b32 v253, s6, 40
	s_lshl_b32 s2, s68, 11
	s_mov_b32 s33, 0x3f317217
	v_writelane_b32 v253, s7, 41
	v_writelane_b32 v253, s2, 42
	s_lshl_b32 s2, s52, 11
	v_writelane_b32 v253, s2, 43
	s_add_u32 s2, s24, 0x8a40400
	s_addc_u32 s3, s25, 0
	v_writelane_b32 v253, s2, 44
	s_load_dwordx16 s[4:19], s[0:1], 0x0
	s_nop 0
	v_writelane_b32 v253, s3, 45
	s_add_u32 s2, s24, 0x4f08000
	v_writelane_b32 v253, s2, 46
	s_addc_u32 s2, s25, 0
	v_writelane_b32 v253, s2, 47
	s_lshl_b32 s2, s68, 7
	s_ashr_i32 s29, s28, 31
	v_writelane_b32 v253, s2, 48
	s_lshl_b32 s2, s52, 7
	v_writelane_b32 v253, s2, 49
	s_lshl_b64 s[2:3], s[28:29], 4
	s_ashr_i32 s57, s56, 31
	v_writelane_b32 v253, s2, 50
	s_nop 1
	v_writelane_b32 v253, s3, 51
	s_lshl_b64 s[2:3], s[56:57], 12
	v_writelane_b32 v253, s2, 52
	s_nop 1
	v_writelane_b32 v253, s3, 53
	s_lshl_b64 s[2:3], s[56:57], 6
	v_writelane_b32 v253, s2, 54
	s_nop 1
	v_writelane_b32 v253, s3, 55
	s_lshl_b64 s[2:3], s[56:57], 11
	v_writelane_b32 v253, s2, 56
	s_nop 1
	v_writelane_b32 v253, s3, 57
	s_waitcnt lgkmcnt(0)
	s_add_u32 s2, s12, 16
	v_writelane_b32 v253, s4, 58
	s_addc_u32 s3, s13, 0
	s_nop 0
	v_writelane_b32 v254, s10, 0
	v_writelane_b32 v254, s11, 1
	v_writelane_b32 v254, s12, 2
	v_writelane_b32 v254, s13, 3
	v_writelane_b32 v254, s14, 4
	v_writelane_b32 v254, s15, 5
	v_writelane_b32 v254, s16, 6
	v_writelane_b32 v254, s17, 7
	v_writelane_b32 v254, s18, 8
	v_writelane_b32 v254, s19, 9
	v_writelane_b32 v254, s2, 10
	s_mov_b64 s[18:19], s[28:29]
	v_writelane_b32 v253, s5, 59
	v_writelane_b32 v254, s3, 11
	s_lshl_b64 s[2:3], s[28:29], 5
	v_writelane_b32 v254, s2, 12
	v_writelane_b32 v253, s6, 60
	v_writelane_b32 v253, s7, 61
	v_writelane_b32 v254, s3, 13
	s_add_u32 s2, s24, 0x162f7000
	s_addc_u32 s3, s25, 0
	v_writelane_b32 v254, s2, 14
	s_mov_b64 s[6:7], vcc
	v_writelane_b32 v253, s8, 62
	v_writelane_b32 v254, s3, 15
	s_lshl_b32 s2, s68, 6
	v_writelane_b32 v254, s2, 16
	s_lshl_b32 s2, s52, 6
	s_mul_i32 s3, s68, 0xc000
	v_writelane_b32 v254, s2, 17
	s_mul_hi_i32 s2, s68, 0xc000
	s_add_u32 s12, s24, s3
	s_addc_u32 s13, s25, s2
	v_writelane_b32 v254, s12, 18
	s_movk_i32 s2, 0x3ff
	v_and_or_b32 v0, v0, s2, v159
	v_writelane_b32 v254, s13, 19
	v_writelane_b32 v254, s74, 20
	s_add_i32 s2, s68, 12
	v_cmp_eq_u32_e64 s[12:13], 0, v0
	v_writelane_b32 v254, s75, 21
	v_writelane_b32 v254, s60, 22
	v_writelane_b32 v253, s9, 63
	s_mov_b64 s[8:9], s[70:71]
	v_writelane_b32 v254, s61, 23
	v_writelane_b32 v254, s2, 24
	s_add_i32 s2, s68, 24
	v_writelane_b32 v254, s2, 25
	s_add_i32 s2, s68, 36
	v_writelane_b32 v254, s2, 26
	s_add_i32 s2, s68, 48
	v_writelane_b32 v254, s2, 27
	s_add_i32 s2, s68, 60
	v_writelane_b32 v254, s2, 28
	s_add_i32 s2, s68, 0x48
	v_writelane_b32 v254, s2, 29
	s_add_i32 s2, s68, 0x54
	v_writelane_b32 v254, s2, 30
	s_lshl_b32 s2, s68, 8
	s_add_i32 s3, s2, 0xfff39c00
	v_writelane_b32 v254, s3, 31
	s_lshl_b32 s3, s52, 8
	v_writelane_b32 v254, s3, 32
	v_writelane_b32 v254, s2, 33
	s_add_i32 s2, s2, 0xfff3a000
	v_writelane_b32 v254, s2, 34
	s_add_i32 s2, s47, 0xb300
	v_writelane_b32 v254, s2, 35
	v_writelane_b32 v254, s47, 36
	s_add_i32 s2, s47, 0xe700
	v_writelane_b32 v254, s2, 37
	s_add_i32 s2, 0, 0x15020
	v_writelane_b32 v254, s2, 38
	s_add_i32 s2, 0, 0xffffc0c0
	v_writelane_b32 v254, s2, 39
	s_add_i32 s2, 0, 0x1ff80
	v_writelane_b32 v254, s2, 40
	s_add_i32 s2, 0, 0x20700
	s_load_dwordx16 s[40:55], s[0:1], 0xc0
	v_writelane_b32 v254, s2, 41
	s_add_i32 s2, 0, 0x20704
	v_writelane_b32 v254, s2, 42
	v_writelane_b32 v254, s12, 43
	s_mov_b64 s[10:11], s[72:73]
	s_mov_b32 s5, 0x800000
	v_writelane_b32 v254, s13, 44
	s_waitcnt lgkmcnt(0)
	v_writelane_b32 v254, s40, 45
	s_mov_b32 s16, 0x21000
	s_movk_i32 s29, 0xff80
	v_writelane_b32 v254, s41, 46
	v_writelane_b32 v254, s42, 47
	v_writelane_b32 v254, s43, 48
	v_writelane_b32 v254, s44, 49
	v_writelane_b32 v254, s45, 50
	v_writelane_b32 v254, s46, 51
	v_writelane_b32 v254, s47, 52
	v_writelane_b32 v254, s48, 53
	v_writelane_b32 v254, s49, 54
	v_writelane_b32 v254, s50, 55
	v_writelane_b32 v254, s51, 56
	v_writelane_b32 v254, s52, 57
	v_writelane_b32 v254, s53, 58
	v_writelane_b32 v254, s54, 59
	v_writelane_b32 v254, s55, 60
	s_load_dwordx16 s[40:55], s[0:1], 0x40
	s_mov_b32 s0, s68
	s_mov_b32 s15, 0xf149f2ca
	s_mov_b32 s3, 0xbfb8aa3b
	s_mov_b32 s14, 0x7f800000
	s_waitcnt lgkmcnt(0)
	v_writelane_b32 v254, s40, 61
	s_mov_b32 s4, 0x3f35f0e3
	s_mov_b32 s2, 0xbe11a98e
	v_writelane_b32 v255, s43, 0
	v_writelane_b32 v255, s44, 1
	v_writelane_b32 v255, s45, 2
	v_writelane_b32 v255, s46, 3
	v_writelane_b32 v255, s47, 4
	v_writelane_b32 v255, s48, 5
	v_writelane_b32 v255, s49, 6
	v_writelane_b32 v255, s50, 7
	v_writelane_b32 v255, s51, 8
	v_writelane_b32 v255, s52, 9
	v_writelane_b32 v255, s53, 10
	v_writelane_b32 v255, s54, 11
	v_writelane_b32 v255, s55, 12
	v_writelane_b32 v255, s0, 13
	v_writelane_b32 v254, s41, 62
	s_mov_b32 s28, 0x3fb8aa3b
	v_writelane_b32 v255, s1, 14
	s_mov_b32 s0, s88
	v_writelane_b32 v255, s0, 15
	v_writelane_b32 v254, s42, 63
	s_nop 0
	v_writelane_b32 v255, s1, 16
	v_writelane_b32 v255, s90, 17
	s_mov_b32 s0, s18
	s_nop 0
	v_writelane_b32 v255, s91, 18
	v_writelane_b32 v255, s96, 19
	s_nop 1
	v_writelane_b32 v255, s97, 20
	v_writelane_b32 v255, s0, 21
	s_nop 1
	v_writelane_b32 v255, s1, 22
	v_writelane_b32 v255, s6, 23
	s_mov_b32 s0, s56
	s_nop 0
	v_writelane_b32 v255, s7, 24
	v_writelane_b32 v255, s8, 25
	s_nop 1
	v_writelane_b32 v255, s9, 26
	v_writelane_b32 v255, s10, 27
	s_nop 1
	v_writelane_b32 v255, s11, 28
	v_writelane_b32 v255, s0, 29
	s_nop 1
	v_writelane_b32 v255, s1, 30
	v_writelane_b32 v255, s64, 31
	s_nop 1
	v_writelane_b32 v255, s65, 32
	v_writelane_b32 v255, s66, 33
	s_nop 1
	v_writelane_b32 v255, s67, 34
	v_writelane_b32 v255, s58, 35
	s_nop 1
	v_writelane_b32 v255, s59, 36
	v_writelane_b32 v255, s78, 37
	s_nop 1
	v_writelane_b32 v255, s79, 38
	s_branch .LBB0_10

.LBB0_37:
	s_add_i32 s69, s48, 2
	s_add_u32 s46, s0, 0x100
	s_addc_u32 s47, s1, 0
	s_add_i32 s70, 0, 0x10000
	ds_read_b128 v[140:143], v153
	ds_read_b128 v[144:147], v153 offset:1024
	ds_read_b128 v[148:151], v153 offset:2048
	ds_read_b128 v[168:171], v153 offset:3072
	s_cmp_eq_u32 s12, s48
	s_cselect_b32 s48, s44, s13
	s_cselect_b32 s51, s43, s47
	s_cselect_b32 s50, s42, s46
	s_cselect_b32 s49, s45, s68
	v_lshl_add_u64 v[156:157], s[0:1], 0, v[136:137]
	ds_read_b128 v[172:175], v155
	ds_read_b128 v[176:179], v155 offset:1024
	ds_read_b128 v[180:183], v155 offset:2048
	ds_read_b128 v[184:187], v155 offset:3072
	ds_read_b128 v[188:191], v155 offset:4096
	ds_read_b128 v[192:195], v155 offset:5120
	ds_read_b128 v[196:199], v155 offset:6144
	ds_read_b128 v[224:227], v155 offset:7168
	s_add_i32 m0, s53, 0xc000
	s_nop 0
	global_load_lds_dwordx4 v[156:157], off
	v_lshl_add_u64 v[156:157], s[0:1], 0, v[138:139]
	s_add_i32 m0, s53, 0xe000
	s_add_i32 s71, 0, 0x14000
	global_load_lds_dwordx4 v[156:157], off
	s_add_i32 s0, s70, s52
	ds_read_b128 v[228:231], v153 offset:16384
	ds_read_b128 v[232:235], v153 offset:17408
	ds_read_b128 v[236:239], v153 offset:18432
	ds_read_b128 v[240:243], v153 offset:19456
	s_waitcnt lgkmcnt(0)
	s_barrier
	v_mfma_f32_16x16x32_bf16 v[126:129], v[140:143], v[172:175], v[126:129]
	v_mfma_f32_16x16x32_bf16 v[122:125], v[148:151], v[172:175], v[122:125]
	v_mfma_f32_16x16x32_bf16 v[110:113], v[140:143], v[180:183], v[110:113]
	v_mfma_f32_16x16x32_bf16 v[106:109], v[148:151], v[180:183], v[106:109]
	v_mfma_f32_16x16x32_bf16 v[94:97], v[140:143], v[188:191], v[94:97]
	v_mfma_f32_16x16x32_bf16 v[90:93], v[148:151], v[188:191], v[90:93]
	v_mfma_f32_16x16x32_bf16 v[78:81], v[140:143], v[196:199], v[78:81]
	v_mfma_f32_16x16x32_bf16 v[74:77], v[148:151], v[196:199], v[74:77]
	v_mfma_f32_16x16x32_bf16 v[126:129], v[144:147], v[176:179], v[126:129]
	v_mfma_f32_16x16x32_bf16 v[122:125], v[168:171], v[176:179], v[122:125]
	v_mfma_f32_16x16x32_bf16 v[110:113], v[144:147], v[184:187], v[110:113]
	v_mfma_f32_16x16x32_bf16 v[106:109], v[168:171], v[184:187], v[106:109]
	v_mfma_f32_16x16x32_bf16 v[94:97], v[144:147], v[192:195], v[94:97]
	v_mfma_f32_16x16x32_bf16 v[90:93], v[168:171], v[192:195], v[90:93]
	v_mfma_f32_16x16x32_bf16 v[78:81], v[144:147], v[224:227], v[78:81]
	v_mfma_f32_16x16x32_bf16 v[74:77], v[168:171], v[224:227], v[74:77]
	v_mfma_f32_16x16x32_bf16 v[118:121], v[228:231], v[172:175], v[118:121]
	v_mfma_f32_16x16x32_bf16 v[114:117], v[236:239], v[172:175], v[114:117]
	v_mfma_f32_16x16x32_bf16 v[102:105], v[228:231], v[180:183], v[102:105]
	v_mfma_f32_16x16x32_bf16 v[98:101], v[236:239], v[180:183], v[98:101]
	v_mfma_f32_16x16x32_bf16 v[86:89], v[228:231], v[188:191], v[86:89]
	v_mfma_f32_16x16x32_bf16 v[82:85], v[236:239], v[188:191], v[82:85]
	v_mfma_f32_16x16x32_bf16 v[70:73], v[228:231], v[196:199], v[70:73]
	v_mfma_f32_16x16x32_bf16 v[66:69], v[236:239], v[196:199], v[66:69]
	v_mfma_f32_16x16x32_bf16 v[118:121], v[232:235], v[176:179], v[118:121]
	v_mfma_f32_16x16x32_bf16 v[114:117], v[240:243], v[176:179], v[114:117]
	v_mfma_f32_16x16x32_bf16 v[102:105], v[232:235], v[184:187], v[102:105]
	v_mfma_f32_16x16x32_bf16 v[98:101], v[240:243], v[184:187], v[98:101]
	v_mfma_f32_16x16x32_bf16 v[86:89], v[232:235], v[192:195], v[86:89]
	v_mfma_f32_16x16x32_bf16 v[82:85], v[240:243], v[192:195], v[82:85]
	v_mfma_f32_16x16x32_bf16 v[70:73], v[232:235], v[224:227], v[70:73]
	v_mfma_f32_16x16x32_bf16 v[66:69], v[240:243], v[224:227], v[66:69]
	s_barrier
	s_mov_b32 m0, s53
	s_add_u32 s78, s50, s94
	s_addc_u32 s79, s51, s95
	ds_read_b128 v[172:175], v155 offset:16384
	ds_read_b128 v[176:179], v155 offset:17408
	ds_read_b128 v[180:183], v155 offset:18432
	ds_read_b128 v[184:187], v155 offset:19456
	ds_read_b128 v[188:191], v155 offset:20480
	ds_read_b128 v[192:195], v155 offset:21504
	ds_read_b128 v[196:199], v155 offset:22528
	ds_read_b128 v[224:227], v155 offset:23552
	global_load_lds_dwordx4 v134, s[50:51]
	s_mov_b32 m0, s54
	s_add_u32 s76, s48, s94
	s_addc_u32 s77, s49, s95
	global_load_lds_dwordx4 v132, s[50:51]
	s_mov_b32 m0, s0
	s_nop 0
	global_load_lds_dwordx4 v0, s[48:49]
	s_add_i32 m0, s0, 0x2000
	s_add_u32 s0, s48, 0x160000
	s_addc_u32 s1, s49, 0
	global_load_lds_dwordx4 v130, s[48:49]
	s_add_i32 s70, s71, s52
	s_mov_b32 m0, s70
	s_nop 0
	global_load_lds_dwordx4 v0, s[0:1]
	s_add_i32 m0, s70, 0x2000
	s_nop 0
	global_load_lds_dwordx4 v130, s[0:1]
	s_waitcnt vmcnt(6) lgkmcnt(0)
	s_barrier
	v_mfma_f32_16x16x32_bf16 v[62:65], v[140:143], v[172:175], v[62:65]
	v_mfma_f32_16x16x32_bf16 v[58:61], v[148:151], v[172:175], v[58:61]
	v_mfma_f32_16x16x32_bf16 v[46:49], v[140:143], v[180:183], v[46:49]
	v_mfma_f32_16x16x32_bf16 v[42:45], v[148:151], v[180:183], v[42:45]
	v_mfma_f32_16x16x32_bf16 v[30:33], v[140:143], v[188:191], v[30:33]
	v_mfma_f32_16x16x32_bf16 v[26:29], v[148:151], v[188:191], v[26:29]
	v_mfma_f32_16x16x32_bf16 v[14:17], v[140:143], v[196:199], v[14:17]
	v_mfma_f32_16x16x32_bf16 v[10:13], v[148:151], v[196:199], v[10:13]
	v_mfma_f32_16x16x32_bf16 v[62:65], v[144:147], v[176:179], v[62:65]
	v_mfma_f32_16x16x32_bf16 v[58:61], v[168:171], v[176:179], v[58:61]
	v_mfma_f32_16x16x32_bf16 v[46:49], v[144:147], v[184:187], v[46:49]
	v_mfma_f32_16x16x32_bf16 v[42:45], v[168:171], v[184:187], v[42:45]
	v_mfma_f32_16x16x32_bf16 v[30:33], v[144:147], v[192:195], v[30:33]
	v_mfma_f32_16x16x32_bf16 v[26:29], v[168:171], v[192:195], v[26:29]
	v_mfma_f32_16x16x32_bf16 v[14:17], v[144:147], v[224:227], v[14:17]
	v_mfma_f32_16x16x32_bf16 v[10:13], v[168:171], v[224:227], v[10:13]
	v_mfma_f32_16x16x32_bf16 v[54:57], v[228:231], v[172:175], v[54:57]
	v_mfma_f32_16x16x32_bf16 v[50:53], v[236:239], v[172:175], v[50:53]
	v_mfma_f32_16x16x32_bf16 v[38:41], v[228:231], v[180:183], v[38:41]
	v_mfma_f32_16x16x32_bf16 v[34:37], v[236:239], v[180:183], v[34:37]
	v_mfma_f32_16x16x32_bf16 v[22:25], v[228:231], v[188:191], v[22:25]
	v_mfma_f32_16x16x32_bf16 v[18:21], v[236:239], v[188:191], v[18:21]
	v_mfma_f32_16x16x32_bf16 v[6:9], v[228:231], v[196:199], v[6:9]
	v_mfma_f32_16x16x32_bf16 v[2:5], v[236:239], v[196:199], v[2:5]
	v_mfma_f32_16x16x32_bf16 v[54:57], v[232:235], v[176:179], v[54:57]
	v_mfma_f32_16x16x32_bf16 v[50:53], v[240:243], v[176:179], v[50:53]
	v_mfma_f32_16x16x32_bf16 v[38:41], v[232:235], v[184:187], v[38:41]
	v_mfma_f32_16x16x32_bf16 v[34:37], v[240:243], v[184:187], v[34:37]
	v_mfma_f32_16x16x32_bf16 v[22:25], v[232:235], v[192:195], v[22:25]
	v_mfma_f32_16x16x32_bf16 v[18:21], v[240:243], v[192:195], v[18:21]
	v_mfma_f32_16x16x32_bf16 v[6:9], v[232:235], v[224:227], v[6:9]
	v_mfma_f32_16x16x32_bf16 v[2:5], v[240:243], v[224:227], v[2:5]
	s_barrier
	s_add_i32 s70, 0, 0x18000
	ds_read_b128 v[140:143], v153 offset:32768
	ds_read_b128 v[144:147], v153 offset:33792
	ds_read_b128 v[148:151], v153 offset:34816
	ds_read_b128 v[168:171], v153 offset:35840
	s_add_u32 s0, s50, 0x2c0000
	s_addc_u32 s1, s51, 0
	ds_read_b128 v[172:175], v155 offset:32768
	ds_read_b128 v[176:179], v155 offset:33792
	ds_read_b128 v[180:183], v155 offset:34816
	ds_read_b128 v[184:187], v155 offset:35840
	ds_read_b128 v[188:191], v155 offset:36864
	ds_read_b128 v[192:195], v155 offset:37888
	ds_read_b128 v[196:199], v155 offset:38912
	ds_read_b128 v[224:227], v155 offset:39936
	s_mov_b32 m0, s55
	s_nop 0
	global_load_lds_dwordx4 v134, s[0:1]
	s_mov_b32 m0, s56
	s_add_i32 s50, 0, 0x1c000
	global_load_lds_dwordx4 v132, s[0:1]
	s_add_i32 s0, s70, s52
	ds_read_b128 v[228:231], v153 offset:49152
	ds_read_b128 v[232:235], v153 offset:50176
	ds_read_b128 v[236:239], v153 offset:51200
	ds_read_b128 v[240:243], v153 offset:52224
	s_waitcnt lgkmcnt(0)
	s_barrier
	v_mfma_f32_16x16x32_bf16 v[126:129], v[140:143], v[172:175], v[126:129]
	v_mfma_f32_16x16x32_bf16 v[122:125], v[148:151], v[172:175], v[122:125]
	v_mfma_f32_16x16x32_bf16 v[110:113], v[140:143], v[180:183], v[110:113]
	v_mfma_f32_16x16x32_bf16 v[106:109], v[148:151], v[180:183], v[106:109]
	v_mfma_f32_16x16x32_bf16 v[94:97], v[140:143], v[188:191], v[94:97]
	v_mfma_f32_16x16x32_bf16 v[90:93], v[148:151], v[188:191], v[90:93]
	v_mfma_f32_16x16x32_bf16 v[78:81], v[140:143], v[196:199], v[78:81]
	v_mfma_f32_16x16x32_bf16 v[74:77], v[148:151], v[196:199], v[74:77]
	v_mfma_f32_16x16x32_bf16 v[126:129], v[144:147], v[176:179], v[126:129]
	v_mfma_f32_16x16x32_bf16 v[122:125], v[168:171], v[176:179], v[122:125]
	v_mfma_f32_16x16x32_bf16 v[110:113], v[144:147], v[184:187], v[110:113]
	v_mfma_f32_16x16x32_bf16 v[106:109], v[168:171], v[184:187], v[106:109]
	v_mfma_f32_16x16x32_bf16 v[94:97], v[144:147], v[192:195], v[94:97]
	v_mfma_f32_16x16x32_bf16 v[90:93], v[168:171], v[192:195], v[90:93]
	v_mfma_f32_16x16x32_bf16 v[78:81], v[144:147], v[224:227], v[78:81]
	v_mfma_f32_16x16x32_bf16 v[74:77], v[168:171], v[224:227], v[74:77]
	v_mfma_f32_16x16x32_bf16 v[118:121], v[228:231], v[172:175], v[118:121]
	v_mfma_f32_16x16x32_bf16 v[114:117], v[236:239], v[172:175], v[114:117]
	v_mfma_f32_16x16x32_bf16 v[102:105], v[228:231], v[180:183], v[102:105]
	v_mfma_f32_16x16x32_bf16 v[98:101], v[236:239], v[180:183], v[98:101]
	v_mfma_f32_16x16x32_bf16 v[86:89], v[228:231], v[188:191], v[86:89]
	v_mfma_f32_16x16x32_bf16 v[82:85], v[236:239], v[188:191], v[82:85]
	v_mfma_f32_16x16x32_bf16 v[70:73], v[228:231], v[196:199], v[70:73]
	v_mfma_f32_16x16x32_bf16 v[66:69], v[236:239], v[196:199], v[66:69]
	v_mfma_f32_16x16x32_bf16 v[118:121], v[232:235], v[176:179], v[118:121]
	v_mfma_f32_16x16x32_bf16 v[114:117], v[240:243], v[176:179], v[114:117]
	v_mfma_f32_16x16x32_bf16 v[102:105], v[232:235], v[184:187], v[102:105]
	v_mfma_f32_16x16x32_bf16 v[98:101], v[240:243], v[184:187], v[98:101]
	v_mfma_f32_16x16x32_bf16 v[86:89], v[232:235], v[192:195], v[86:89]
	v_mfma_f32_16x16x32_bf16 v[82:85], v[240:243], v[192:195], v[82:85]
	v_mfma_f32_16x16x32_bf16 v[70:73], v[232:235], v[224:227], v[70:73]
	v_mfma_f32_16x16x32_bf16 v[66:69], v[240:243], v[224:227], v[66:69]
	s_barrier
	s_mov_b32 m0, s57
	ds_read_b128 v[172:175], v155 offset:49152
	ds_read_b128 v[176:179], v155 offset:50176
	ds_read_b128 v[180:183], v155 offset:51200
	ds_read_b128 v[184:187], v155 offset:52224
	ds_read_b128 v[188:191], v155 offset:53248
	ds_read_b128 v[192:195], v155 offset:54272
	ds_read_b128 v[196:199], v155 offset:55296
	ds_read_b128 v[224:227], v155 offset:56320
	global_load_lds_dwordx4 v134, s[78:79]
	s_mov_b32 m0, s58
	s_nop 0
	global_load_lds_dwordx4 v132, s[78:79]
	s_mov_b32 m0, s0
	s_nop 0
	global_load_lds_dwordx4 v0, s[76:77]
	s_add_i32 m0, s0, 0x2000
	s_add_u32 s0, s48, 0x160080
	s_addc_u32 s1, s49, 0
	global_load_lds_dwordx4 v130, s[76:77]
	s_add_i32 s48, s50, s52
	s_mov_b32 m0, s48
	s_nop 0
	global_load_lds_dwordx4 v0, s[0:1]
	s_add_i32 m0, s48, 0x2000
	s_nop 0
	global_load_lds_dwordx4 v130, s[0:1]
	s_waitcnt vmcnt(6) lgkmcnt(0)
	s_barrier
	v_mfma_f32_16x16x32_bf16 v[62:65], v[140:143], v[172:175], v[62:65]
	v_mfma_f32_16x16x32_bf16 v[58:61], v[148:151], v[172:175], v[58:61]
	v_mfma_f32_16x16x32_bf16 v[46:49], v[140:143], v[180:183], v[46:49]
	v_mfma_f32_16x16x32_bf16 v[42:45], v[148:151], v[180:183], v[42:45]
	v_mfma_f32_16x16x32_bf16 v[30:33], v[140:143], v[188:191], v[30:33]
	v_mfma_f32_16x16x32_bf16 v[26:29], v[148:151], v[188:191], v[26:29]
	v_mfma_f32_16x16x32_bf16 v[14:17], v[140:143], v[196:199], v[14:17]
	v_mfma_f32_16x16x32_bf16 v[10:13], v[148:151], v[196:199], v[10:13]
	v_mfma_f32_16x16x32_bf16 v[62:65], v[144:147], v[176:179], v[62:65]
	v_mfma_f32_16x16x32_bf16 v[58:61], v[168:171], v[176:179], v[58:61]
	v_mfma_f32_16x16x32_bf16 v[46:49], v[144:147], v[184:187], v[46:49]
	v_mfma_f32_16x16x32_bf16 v[42:45], v[168:171], v[184:187], v[42:45]
	v_mfma_f32_16x16x32_bf16 v[30:33], v[144:147], v[192:195], v[30:33]
	v_mfma_f32_16x16x32_bf16 v[26:29], v[168:171], v[192:195], v[26:29]
	v_mfma_f32_16x16x32_bf16 v[14:17], v[144:147], v[224:227], v[14:17]
	v_mfma_f32_16x16x32_bf16 v[10:13], v[168:171], v[224:227], v[10:13]
	v_mfma_f32_16x16x32_bf16 v[54:57], v[228:231], v[172:175], v[54:57]
	v_mfma_f32_16x16x32_bf16 v[50:53], v[236:239], v[172:175], v[50:53]
	v_mfma_f32_16x16x32_bf16 v[38:41], v[228:231], v[180:183], v[38:41]
	v_mfma_f32_16x16x32_bf16 v[34:37], v[236:239], v[180:183], v[34:37]
	v_mfma_f32_16x16x32_bf16 v[22:25], v[228:231], v[188:191], v[22:25]
	v_mfma_f32_16x16x32_bf16 v[18:21], v[236:239], v[188:191], v[18:21]
	v_mfma_f32_16x16x32_bf16 v[6:9], v[228:231], v[196:199], v[6:9]
	v_mfma_f32_16x16x32_bf16 v[2:5], v[236:239], v[196:199], v[2:5]
	v_mfma_f32_16x16x32_bf16 v[54:57], v[232:235], v[176:179], v[54:57]
	v_mfma_f32_16x16x32_bf16 v[50:53], v[240:243], v[176:179], v[50:53]
	v_mfma_f32_16x16x32_bf16 v[38:41], v[232:235], v[184:187], v[38:41]
	v_mfma_f32_16x16x32_bf16 v[34:37], v[240:243], v[184:187], v[34:37]
	v_mfma_f32_16x16x32_bf16 v[22:25], v[232:235], v[192:195], v[22:25]
	v_mfma_f32_16x16x32_bf16 v[18:21], v[240:243], v[192:195], v[18:21]
	v_mfma_f32_16x16x32_bf16 v[6:9], v[232:235], v[224:227], v[6:9]
	v_mfma_f32_16x16x32_bf16 v[2:5], v[240:243], v[224:227], v[2:5]
	s_barrier
	s_add_u32 s13, s13, 0x100
	s_addc_u32 s68, s68, 0
	s_mov_b64 s[0:1], s[46:47]
	s_mov_b32 s48, s69
	s_cmp_ge_i32 s69, s39
	s_cbranch_scc0 .LBB0_37
	s_cmp_eq_u32 s65, 2
	s_cbranch_scc1 .Lepi10_orig
	v_readlane_b32 s90, v255, 17
	v_readlane_b32 s91, v255, 18
	v_readlane_b32 s96, v255, 19
	v_readlane_b32 s97, v255, 20
	v_lshl_or_b32 v156, s66, 8, v154
	v_lshlrev_b32_e32 v156, 2, v156
	v_lshl_add_u32 v157, v152, 13, v156
	s_lshl_b32 s72, s67, 21
	s_add_u32 s74, s22, s72
	s_addc_u32 s75, s23, 0
	s_add_u32 s76, s22, s72
	s_addc_u32 s77, s23, 0
	s_lshr_b32 s73, s67, 3
	s_mul_i32 s73, s73, 0xc000
	s_add_u32 s73, s73, 0xa000
	s_add_u32 s70, s90, s73
	s_addc_u32 s71, s91, 0
	global_load_dwordx4 v[140:143], v156, s[70:71]
	global_load_dwordx4 v[144:147], v156, s[70:71] offset:64
	global_load_dwordx4 v[148:151], v156, s[70:71] offset:512
	global_load_dwordx4 v[168:171], v156, s[70:71] offset:576
	global_load_dwordx4 v[224:227], v157, s[74:75] nt
	global_load_dwordx4 v[228:231], v157, s[74:75] offset:64 nt
	global_load_dwordx4 v[232:235], v157, s[74:75] offset:512 nt
	global_load_dwordx4 v[236:239], v157, s[74:75] offset:576 nt
	s_add_u32 s74, s74, 0x20000
	s_addc_u32 s75, s75, 0
	global_load_dwordx4 v[240:243], v157, s[74:75] nt
	global_load_dwordx4 v[244:247], v157, s[74:75] offset:64 nt
	s_waitcnt vmcnt(5)
	v_pk_fma_f32 v[128:129], v[128:129], v[142:143], v[226:227]
	v_pk_fma_f32 v[126:127], v[126:127], v[140:141], v[224:225]
	global_store_dwordx4 v157, v[126:129], s[76:77] nt
	global_load_dwordx4 v[224:227], v157, s[74:75] offset:512 nt
	s_waitcnt vmcnt(6)
	v_pk_fma_f32 v[124:125], v[124:125], v[146:147], v[230:231]
	v_pk_fma_f32 v[122:123], v[122:123], v[144:145], v[228:229]
	global_store_dwordx4 v157, v[122:125], s[76:77] offset:64 nt
	global_load_dwordx4 v[228:231], v157, s[74:75] offset:576 nt
	s_waitcnt vmcnt(7)
	v_pk_fma_f32 v[120:121], v[120:121], v[150:151], v[234:235]
	v_pk_fma_f32 v[118:119], v[118:119], v[148:149], v[232:233]
	global_store_dwordx4 v157, v[118:121], s[76:77] offset:512 nt
	s_add_u32 s74, s74, 0x20000
	s_addc_u32 s75, s75, 0
	global_load_dwordx4 v[232:235], v157, s[74:75] nt
	s_waitcnt vmcnt(8)
	v_pk_fma_f32 v[116:117], v[116:117], v[170:171], v[238:239]
	v_pk_fma_f32 v[114:115], v[114:115], v[168:169], v[236:237]
	global_store_dwordx4 v157, v[114:117], s[76:77] offset:576 nt
	global_load_dwordx4 v[236:239], v157, s[74:75] offset:64 nt
	s_add_u32 s76, s76, 0x20000
	s_addc_u32 s77, s77, 0
	s_waitcnt vmcnt(9)
	v_pk_fma_f32 v[112:113], v[112:113], v[142:143], v[242:243]
	v_pk_fma_f32 v[110:111], v[110:111], v[140:141], v[240:241]
	global_store_dwordx4 v157, v[110:113], s[76:77] nt
	global_load_dwordx4 v[240:243], v157, s[74:75] offset:512 nt
	s_waitcnt vmcnt(10)
	v_pk_fma_f32 v[108:109], v[108:109], v[146:147], v[246:247]
	v_pk_fma_f32 v[106:107], v[106:107], v[144:145], v[244:245]
	global_store_dwordx4 v157, v[106:109], s[76:77] offset:64 nt
	global_load_dwordx4 v[244:247], v157, s[74:75] offset:576 nt
	s_waitcnt vmcnt(10)
	v_pk_fma_f32 v[104:105], v[104:105], v[150:151], v[226:227]
	v_pk_fma_f32 v[102:103], v[102:103], v[148:149], v[224:225]
	global_store_dwordx4 v157, v[102:105], s[76:77] offset:512 nt
	s_add_u32 s74, s74, 0x20000
	s_addc_u32 s75, s75, 0
	global_load_dwordx4 v[224:227], v157, s[74:75] nt
	s_waitcnt vmcnt(10)
	v_pk_fma_f32 v[100:101], v[100:101], v[170:171], v[230:231]
	v_pk_fma_f32 v[98:99], v[98:99], v[168:169], v[228:229]
	global_store_dwordx4 v157, v[98:101], s[76:77] offset:576 nt
	global_load_dwordx4 v[228:231], v157, s[74:75] offset:64 nt
	s_add_u32 s76, s76, 0x20000
	s_addc_u32 s77, s77, 0
	s_waitcnt vmcnt(10)
	v_pk_fma_f32 v[96:97], v[96:97], v[142:143], v[234:235]
	v_pk_fma_f32 v[94:95], v[94:95], v[140:141], v[232:233]
	global_store_dwordx4 v157, v[94:97], s[76:77] nt
	global_load_dwordx4 v[232:235], v157, s[74:75] offset:512 nt
	s_waitcnt vmcnt(10)
	v_pk_fma_f32 v[92:93], v[92:93], v[146:147], v[238:239]
	v_pk_fma_f32 v[90:91], v[90:91], v[144:145], v[236:237]
	global_store_dwordx4 v157, v[90:93], s[76:77] offset:64 nt
	global_load_dwordx4 v[236:239], v157, s[74:75] offset:576 nt
	s_waitcnt vmcnt(10)
	v_pk_fma_f32 v[88:89], v[88:89], v[150:151], v[242:243]
	v_pk_fma_f32 v[86:87], v[86:87], v[148:149], v[240:241]
	global_store_dwordx4 v157, v[86:89], s[76:77] offset:512 nt
	s_add_u32 s74, s74, 0xa0000
	s_addc_u32 s75, s75, 0
	global_load_dwordx4 v[240:243], v157, s[74:75] nt
	s_waitcnt vmcnt(10)
	v_pk_fma_f32 v[84:85], v[84:85], v[170:171], v[246:247]
	v_pk_fma_f32 v[82:83], v[82:83], v[168:169], v[244:245]
	global_store_dwordx4 v157, v[82:85], s[76:77] offset:576 nt
	global_load_dwordx4 v[244:247], v157, s[74:75] offset:64 nt
	s_add_u32 s76, s76, 0x20000
	s_addc_u32 s77, s77, 0
	s_waitcnt vmcnt(10)
	v_pk_fma_f32 v[80:81], v[80:81], v[142:143], v[226:227]
	v_pk_fma_f32 v[78:79], v[78:79], v[140:141], v[224:225]
	global_store_dwordx4 v157, v[78:81], s[76:77] nt
	global_load_dwordx4 v[224:227], v157, s[74:75] offset:512 nt
	s_waitcnt vmcnt(10)
	v_pk_fma_f32 v[76:77], v[76:77], v[146:147], v[230:231]
	v_pk_fma_f32 v[74:75], v[74:75], v[144:145], v[228:229]
	global_store_dwordx4 v157, v[74:77], s[76:77] offset:64 nt
	global_load_dwordx4 v[228:231], v157, s[74:75] offset:576 nt
	s_waitcnt vmcnt(10)
	v_pk_fma_f32 v[72:73], v[72:73], v[150:151], v[234:235]
	v_pk_fma_f32 v[70:71], v[70:71], v[148:149], v[232:233]
	global_store_dwordx4 v157, v[70:73], s[76:77] offset:512 nt
	s_add_u32 s74, s74, 0x20000
	s_addc_u32 s75, s75, 0
	global_load_dwordx4 v[232:235], v157, s[74:75] nt
	s_waitcnt vmcnt(10)
	v_pk_fma_f32 v[68:69], v[68:69], v[170:171], v[238:239]
	v_pk_fma_f32 v[66:67], v[66:67], v[168:169], v[236:237]
	global_store_dwordx4 v157, v[66:69], s[76:77] offset:576 nt
	global_load_dwordx4 v[236:239], v157, s[74:75] offset:64 nt
	s_add_u32 s76, s76, 0xa0000
	s_addc_u32 s77, s77, 0
	s_waitcnt vmcnt(10)
	v_pk_fma_f32 v[64:65], v[64:65], v[142:143], v[242:243]
	v_pk_fma_f32 v[62:63], v[62:63], v[140:141], v[240:241]
	global_store_dwordx4 v157, v[62:65], s[76:77] nt
	global_load_dwordx4 v[240:243], v157, s[74:75] offset:512 nt
	s_waitcnt vmcnt(10)
	v_pk_fma_f32 v[60:61], v[60:61], v[146:147], v[246:247]
	v_pk_fma_f32 v[58:59], v[58:59], v[144:145], v[244:245]
	global_store_dwordx4 v157, v[58:61], s[76:77] offset:64 nt
	global_load_dwordx4 v[244:247], v157, s[74:75] offset:576 nt
	s_waitcnt vmcnt(10)
	v_pk_fma_f32 v[56:57], v[56:57], v[150:151], v[226:227]
	v_pk_fma_f32 v[54:55], v[54:55], v[148:149], v[224:225]
	global_store_dwordx4 v157, v[54:57], s[76:77] offset:512 nt
	s_add_u32 s74, s74, 0x20000
	s_addc_u32 s75, s75, 0
	global_load_dwordx4 v[224:227], v157, s[74:75] nt
	s_waitcnt vmcnt(10)
	v_pk_fma_f32 v[52:53], v[52:53], v[170:171], v[230:231]
	v_pk_fma_f32 v[50:51], v[50:51], v[168:169], v[228:229]
	global_store_dwordx4 v157, v[50:53], s[76:77] offset:576 nt
	global_load_dwordx4 v[228:231], v157, s[74:75] offset:64 nt
	s_add_u32 s76, s76, 0x20000
	s_addc_u32 s77, s77, 0
	s_waitcnt vmcnt(10)
	v_pk_fma_f32 v[48:49], v[48:49], v[142:143], v[234:235]
	v_pk_fma_f32 v[46:47], v[46:47], v[140:141], v[232:233]
	global_store_dwordx4 v157, v[46:49], s[76:77] nt
	global_load_dwordx4 v[232:235], v157, s[74:75] offset:512 nt
	s_waitcnt vmcnt(10)
	v_pk_fma_f32 v[44:45], v[44:45], v[146:147], v[238:239]
	v_pk_fma_f32 v[42:43], v[42:43], v[144:145], v[236:237]
	global_store_dwordx4 v157, v[42:45], s[76:77] offset:64 nt
	global_load_dwordx4 v[236:239], v157, s[74:75] offset:576 nt
	s_waitcnt vmcnt(10)
	v_pk_fma_f32 v[40:41], v[40:41], v[150:151], v[242:243]
	v_pk_fma_f32 v[38:39], v[38:39], v[148:149], v[240:241]
	global_store_dwordx4 v157, v[38:41], s[76:77] offset:512 nt
	s_add_u32 s74, s74, 0x20000
	s_addc_u32 s75, s75, 0
	global_load_dwordx4 v[240:243], v157, s[74:75] nt
	s_waitcnt vmcnt(10)
	v_pk_fma_f32 v[36:37], v[36:37], v[170:171], v[246:247]
	v_pk_fma_f32 v[34:35], v[34:35], v[168:169], v[244:245]
	global_store_dwordx4 v157, v[34:37], s[76:77] offset:576 nt
	global_load_dwordx4 v[244:247], v157, s[74:75] offset:64 nt
	s_add_u32 s76, s76, 0x20000
	s_addc_u32 s77, s77, 0
	s_waitcnt vmcnt(10)
	v_pk_fma_f32 v[32:33], v[32:33], v[142:143], v[226:227]
	v_pk_fma_f32 v[30:31], v[30:31], v[140:141], v[224:225]
	global_store_dwordx4 v157, v[30:33], s[76:77] nt
	global_load_dwordx4 v[224:227], v157, s[74:75] offset:512 nt
	s_waitcnt vmcnt(10)
	v_pk_fma_f32 v[28:29], v[28:29], v[146:147], v[230:231]
	v_pk_fma_f32 v[26:27], v[26:27], v[144:145], v[228:229]
	global_store_dwordx4 v157, v[26:29], s[76:77] offset:64 nt
	global_load_dwordx4 v[228:231], v157, s[74:75] offset:576 nt
	s_waitcnt vmcnt(10)
	v_pk_fma_f32 v[24:25], v[24:25], v[150:151], v[234:235]
	v_pk_fma_f32 v[22:23], v[22:23], v[148:149], v[232:233]
	global_store_dwordx4 v157, v[22:25], s[76:77] offset:512 nt
	s_waitcnt vmcnt(9)
	v_pk_fma_f32 v[20:21], v[20:21], v[170:171], v[238:239]
	v_pk_fma_f32 v[18:19], v[18:19], v[168:169], v[236:237]
	global_store_dwordx4 v157, v[18:21], s[76:77] offset:576 nt
	s_add_u32 s76, s76, 0x20000
	s_addc_u32 s77, s77, 0
	s_waitcnt vmcnt(8)
	v_pk_fma_f32 v[16:17], v[16:17], v[142:143], v[242:243]
	v_pk_fma_f32 v[14:15], v[14:15], v[140:141], v[240:241]
	global_store_dwordx4 v157, v[14:17], s[76:77] nt
	s_waitcnt vmcnt(7)
	v_pk_fma_f32 v[12:13], v[12:13], v[146:147], v[246:247]
	v_pk_fma_f32 v[10:11], v[10:11], v[144:145], v[244:245]
	global_store_dwordx4 v157, v[10:13], s[76:77] offset:64 nt
	s_waitcnt vmcnt(6)
	v_pk_fma_f32 v[8:9], v[8:9], v[150:151], v[226:227]
	v_pk_fma_f32 v[6:7], v[6:7], v[148:149], v[224:225]
	global_store_dwordx4 v157, v[6:9], s[76:77] offset:512 nt
	s_waitcnt vmcnt(5)
	v_pk_fma_f32 v[4:5], v[4:5], v[170:171], v[230:231]
	v_pk_fma_f32 v[2:3], v[2:3], v[168:169], v[228:229]
	global_store_dwordx4 v157, v[2:5], s[76:77] offset:576 nt
	s_branch .LBB0_24

.LBB0_231:
	s_cmpk_gt_i32 s1, 0x4ff
	s_cbranch_scc1 .Lp8_noperm
	s_and_b32 s0, s1, 7
	s_lshl_b32 s0, s0, 5
	s_bfe_u32 s12, s1, 0x50003
	s_and_b32 s1, s1, 0xffffff00
	s_or_b32 s1, s1, s0
	s_or_b32 s1, s1, s12

.LBB0_234:
	s_add_u32 s39, s46, 0xfff80080
	s_addc_u32 s48, s47, -1
	s_add_i32 s62, 0, 0x10000
	ds_read_b128 v[144:147], v141
	ds_read_b128 v[148:151], v141 offset:1024
	ds_read_b128 v[152:155], v141 offset:2048
	ds_read_b128 v[168:171], v141 offset:3072
	s_cmp_eq_u32 s13, 28
	s_cselect_b32 s51, s43, s48
	s_cselect_b32 s50, s42, s39
	s_cselect_b32 s49, s45, s12
	s_cselect_b32 s48, s44, s1
	ds_read_b128 v[172:175], v143
	ds_read_b128 v[176:179], v143 offset:1024
	ds_read_b128 v[180:183], v143 offset:2048
	ds_read_b128 v[184:187], v143 offset:3072
	ds_read_b128 v[188:191], v143 offset:4096
	ds_read_b128 v[192:195], v143 offset:5120
	ds_read_b128 v[196:199], v143 offset:6144
	ds_read_b128 v[224:227], v143 offset:7168
	s_add_i32 m0, s53, 0xc000
	s_nop 0
	global_load_lds_dwordx4 v136, s[46:47]
	s_add_i32 m0, s53, 0xe000
	s_add_i32 s39, 0, 0x14000
	global_load_lds_dwordx4 v138, s[46:47]
	s_add_i32 s62, s62, s52
	ds_read_b128 v[228:231], v141 offset:16384
	ds_read_b128 v[232:235], v141 offset:17408
	ds_read_b128 v[236:239], v141 offset:18432
	ds_read_b128 v[240:243], v141 offset:19456
	s_waitcnt lgkmcnt(0)
	s_barrier
	v_mfma_f32_16x16x32_bf16 v[126:129], v[144:147], v[172:175], v[126:129]
	v_mfma_f32_16x16x32_bf16 v[122:125], v[152:155], v[172:175], v[122:125]
	v_mfma_f32_16x16x32_bf16 v[118:121], v[144:147], v[180:183], v[118:121]
	v_mfma_f32_16x16x32_bf16 v[114:117], v[152:155], v[180:183], v[114:117]
	v_mfma_f32_16x16x32_bf16 v[102:105], v[144:147], v[188:191], v[102:105]
	v_mfma_f32_16x16x32_bf16 v[98:101], v[152:155], v[188:191], v[98:101]
	v_mfma_f32_16x16x32_bf16 v[86:89], v[144:147], v[196:199], v[86:89]
	v_mfma_f32_16x16x32_bf16 v[82:85], v[152:155], v[196:199], v[82:85]
	v_mfma_f32_16x16x32_bf16 v[126:129], v[148:151], v[176:179], v[126:129]
	v_mfma_f32_16x16x32_bf16 v[122:125], v[168:171], v[176:179], v[122:125]
	v_mfma_f32_16x16x32_bf16 v[118:121], v[148:151], v[184:187], v[118:121]
	v_mfma_f32_16x16x32_bf16 v[114:117], v[168:171], v[184:187], v[114:117]
	v_mfma_f32_16x16x32_bf16 v[102:105], v[148:151], v[192:195], v[102:105]
	v_mfma_f32_16x16x32_bf16 v[98:101], v[168:171], v[192:195], v[98:101]
	v_mfma_f32_16x16x32_bf16 v[86:89], v[148:151], v[224:227], v[86:89]
	v_mfma_f32_16x16x32_bf16 v[82:85], v[168:171], v[224:227], v[82:85]
	v_mfma_f32_16x16x32_bf16 v[110:113], v[228:231], v[172:175], v[110:113]
	v_mfma_f32_16x16x32_bf16 v[106:109], v[236:239], v[172:175], v[106:109]
	v_mfma_f32_16x16x32_bf16 v[94:97], v[228:231], v[180:183], v[94:97]
	v_mfma_f32_16x16x32_bf16 v[90:93], v[236:239], v[180:183], v[90:93]
	v_mfma_f32_16x16x32_bf16 v[78:81], v[228:231], v[188:191], v[78:81]
	v_mfma_f32_16x16x32_bf16 v[74:77], v[236:239], v[188:191], v[74:77]
	v_mfma_f32_16x16x32_bf16 v[70:73], v[228:231], v[196:199], v[70:73]
	v_mfma_f32_16x16x32_bf16 v[66:69], v[236:239], v[196:199], v[66:69]
	v_mfma_f32_16x16x32_bf16 v[110:113], v[232:235], v[176:179], v[110:113]
	v_mfma_f32_16x16x32_bf16 v[106:109], v[240:243], v[176:179], v[106:109]
	v_mfma_f32_16x16x32_bf16 v[94:97], v[232:235], v[184:187], v[94:97]
	v_mfma_f32_16x16x32_bf16 v[90:93], v[240:243], v[184:187], v[90:93]
	v_mfma_f32_16x16x32_bf16 v[78:81], v[232:235], v[192:195], v[78:81]
	v_mfma_f32_16x16x32_bf16 v[74:77], v[240:243], v[192:195], v[74:77]
	v_mfma_f32_16x16x32_bf16 v[70:73], v[232:235], v[224:227], v[70:73]
	v_mfma_f32_16x16x32_bf16 v[66:69], v[240:243], v[224:227], v[66:69]
	s_barrier
	s_mov_b32 m0, s53
	s_add_u32 s78, s50, s94
	s_addc_u32 s79, s51, s95
	ds_read_b128 v[172:175], v143 offset:16384
	ds_read_b128 v[176:179], v143 offset:17408
	ds_read_b128 v[180:183], v143 offset:18432
	ds_read_b128 v[184:187], v143 offset:19456
	ds_read_b128 v[188:191], v143 offset:20480
	ds_read_b128 v[192:195], v143 offset:21504
	ds_read_b128 v[196:199], v143 offset:22528
	ds_read_b128 v[224:227], v143 offset:23552
	global_load_lds_dwordx4 v134, s[50:51]
	s_mov_b32 m0, s54
	s_add_u32 s76, s48, s94
	s_addc_u32 s77, s49, s95
	global_load_lds_dwordx4 v132, s[50:51]
	s_mov_b32 m0, s62
	s_nop 0
	global_load_lds_dwordx4 v0, s[48:49]
	s_add_i32 m0, s62, 0x2000
	s_add_u32 s62, s48, 0x80000
	s_addc_u32 s63, s49, 0
	global_load_lds_dwordx4 v130, s[48:49]
	s_add_i32 s39, s39, s52
	s_mov_b32 m0, s39
	s_nop 0
	global_load_lds_dwordx4 v0, s[62:63]
	s_add_i32 m0, s39, 0x2000
	s_nop 0
	global_load_lds_dwordx4 v130, s[62:63]
	s_waitcnt vmcnt(6) lgkmcnt(0)
	s_barrier
	v_mfma_f32_16x16x32_bf16 v[62:65], v[144:147], v[172:175], v[62:65]
	v_mfma_f32_16x16x32_bf16 v[58:61], v[152:155], v[172:175], v[58:61]
	v_mfma_f32_16x16x32_bf16 v[54:57], v[144:147], v[180:183], v[54:57]
	v_mfma_f32_16x16x32_bf16 v[50:53], v[152:155], v[180:183], v[50:53]
	v_mfma_f32_16x16x32_bf16 v[38:41], v[144:147], v[188:191], v[38:41]
	v_mfma_f32_16x16x32_bf16 v[34:37], v[152:155], v[188:191], v[34:37]
	v_mfma_f32_16x16x32_bf16 v[22:25], v[144:147], v[196:199], v[22:25]
	v_mfma_f32_16x16x32_bf16 v[18:21], v[152:155], v[196:199], v[18:21]
	v_mfma_f32_16x16x32_bf16 v[62:65], v[148:151], v[176:179], v[62:65]
	v_mfma_f32_16x16x32_bf16 v[58:61], v[168:171], v[176:179], v[58:61]
	v_mfma_f32_16x16x32_bf16 v[54:57], v[148:151], v[184:187], v[54:57]
	v_mfma_f32_16x16x32_bf16 v[50:53], v[168:171], v[184:187], v[50:53]
	v_mfma_f32_16x16x32_bf16 v[38:41], v[148:151], v[192:195], v[38:41]
	v_mfma_f32_16x16x32_bf16 v[34:37], v[168:171], v[192:195], v[34:37]
	v_mfma_f32_16x16x32_bf16 v[22:25], v[148:151], v[224:227], v[22:25]
	v_mfma_f32_16x16x32_bf16 v[18:21], v[168:171], v[224:227], v[18:21]
	v_mfma_f32_16x16x32_bf16 v[46:49], v[228:231], v[172:175], v[46:49]
	v_mfma_f32_16x16x32_bf16 v[42:45], v[236:239], v[172:175], v[42:45]
	v_mfma_f32_16x16x32_bf16 v[30:33], v[228:231], v[180:183], v[30:33]
	v_mfma_f32_16x16x32_bf16 v[26:29], v[236:239], v[180:183], v[26:29]
	v_mfma_f32_16x16x32_bf16 v[14:17], v[228:231], v[188:191], v[14:17]
	v_mfma_f32_16x16x32_bf16 v[10:13], v[236:239], v[188:191], v[10:13]
	v_mfma_f32_16x16x32_bf16 v[6:9], v[228:231], v[196:199], v[6:9]
	v_mfma_f32_16x16x32_bf16 v[2:5], v[236:239], v[196:199], v[2:5]
	v_mfma_f32_16x16x32_bf16 v[46:49], v[232:235], v[176:179], v[46:49]
	v_mfma_f32_16x16x32_bf16 v[42:45], v[240:243], v[176:179], v[42:45]
	v_mfma_f32_16x16x32_bf16 v[30:33], v[232:235], v[184:187], v[30:33]
	v_mfma_f32_16x16x32_bf16 v[26:29], v[240:243], v[184:187], v[26:29]
	v_mfma_f32_16x16x32_bf16 v[14:17], v[232:235], v[192:195], v[14:17]
	v_mfma_f32_16x16x32_bf16 v[10:13], v[240:243], v[192:195], v[10:13]
	v_mfma_f32_16x16x32_bf16 v[6:9], v[232:235], v[224:227], v[6:9]
	v_mfma_f32_16x16x32_bf16 v[2:5], v[240:243], v[224:227], v[2:5]
	s_barrier
	s_add_i32 s39, 0, 0x18000
	ds_read_b128 v[144:147], v141 offset:32768
	ds_read_b128 v[148:151], v141 offset:33792
	ds_read_b128 v[152:155], v141 offset:34816
	ds_read_b128 v[168:171], v141 offset:35840
	s_add_u32 s50, s50, 0x80000
	s_addc_u32 s51, s51, 0
	ds_read_b128 v[172:175], v143 offset:32768
	ds_read_b128 v[176:179], v143 offset:33792
	ds_read_b128 v[180:183], v143 offset:34816
	ds_read_b128 v[184:187], v143 offset:35840
	ds_read_b128 v[188:191], v143 offset:36864
	ds_read_b128 v[192:195], v143 offset:37888
	ds_read_b128 v[196:199], v143 offset:38912
	ds_read_b128 v[224:227], v143 offset:39936
	s_mov_b32 m0, s55
	s_nop 0
	global_load_lds_dwordx4 v134, s[50:51]
	s_mov_b32 m0, s56
	s_nop 0
	global_load_lds_dwordx4 v132, s[50:51]
	s_add_i32 s50, 0, 0x1c000
	s_add_i32 s39, s39, s52
	ds_read_b128 v[228:231], v141 offset:49152
	ds_read_b128 v[232:235], v141 offset:50176
	ds_read_b128 v[236:239], v141 offset:51200
	ds_read_b128 v[240:243], v141 offset:52224
	s_waitcnt lgkmcnt(0)
	s_barrier
	v_mfma_f32_16x16x32_bf16 v[126:129], v[144:147], v[172:175], v[126:129]
	v_mfma_f32_16x16x32_bf16 v[122:125], v[152:155], v[172:175], v[122:125]
	v_mfma_f32_16x16x32_bf16 v[118:121], v[144:147], v[180:183], v[118:121]
	v_mfma_f32_16x16x32_bf16 v[114:117], v[152:155], v[180:183], v[114:117]
	v_mfma_f32_16x16x32_bf16 v[102:105], v[144:147], v[188:191], v[102:105]
	v_mfma_f32_16x16x32_bf16 v[98:101], v[152:155], v[188:191], v[98:101]
	v_mfma_f32_16x16x32_bf16 v[86:89], v[144:147], v[196:199], v[86:89]
	v_mfma_f32_16x16x32_bf16 v[82:85], v[152:155], v[196:199], v[82:85]
	v_mfma_f32_16x16x32_bf16 v[126:129], v[148:151], v[176:179], v[126:129]
	v_mfma_f32_16x16x32_bf16 v[122:125], v[168:171], v[176:179], v[122:125]
	v_mfma_f32_16x16x32_bf16 v[118:121], v[148:151], v[184:187], v[118:121]
	v_mfma_f32_16x16x32_bf16 v[114:117], v[168:171], v[184:187], v[114:117]
	v_mfma_f32_16x16x32_bf16 v[102:105], v[148:151], v[192:195], v[102:105]
	v_mfma_f32_16x16x32_bf16 v[98:101], v[168:171], v[192:195], v[98:101]
	v_mfma_f32_16x16x32_bf16 v[86:89], v[148:151], v[224:227], v[86:89]
	v_mfma_f32_16x16x32_bf16 v[82:85], v[168:171], v[224:227], v[82:85]
	v_mfma_f32_16x16x32_bf16 v[110:113], v[228:231], v[172:175], v[110:113]
	v_mfma_f32_16x16x32_bf16 v[106:109], v[236:239], v[172:175], v[106:109]
	v_mfma_f32_16x16x32_bf16 v[94:97], v[228:231], v[180:183], v[94:97]
	v_mfma_f32_16x16x32_bf16 v[90:93], v[236:239], v[180:183], v[90:93]
	v_mfma_f32_16x16x32_bf16 v[78:81], v[228:231], v[188:191], v[78:81]
	v_mfma_f32_16x16x32_bf16 v[74:77], v[236:239], v[188:191], v[74:77]
	v_mfma_f32_16x16x32_bf16 v[70:73], v[228:231], v[196:199], v[70:73]
	v_mfma_f32_16x16x32_bf16 v[66:69], v[236:239], v[196:199], v[66:69]
	v_mfma_f32_16x16x32_bf16 v[110:113], v[232:235], v[176:179], v[110:113]
	v_mfma_f32_16x16x32_bf16 v[106:109], v[240:243], v[176:179], v[106:109]
	v_mfma_f32_16x16x32_bf16 v[94:97], v[232:235], v[184:187], v[94:97]
	v_mfma_f32_16x16x32_bf16 v[90:93], v[240:243], v[184:187], v[90:93]
	v_mfma_f32_16x16x32_bf16 v[78:81], v[232:235], v[192:195], v[78:81]
	v_mfma_f32_16x16x32_bf16 v[74:77], v[240:243], v[192:195], v[74:77]
	v_mfma_f32_16x16x32_bf16 v[70:73], v[232:235], v[224:227], v[70:73]
	v_mfma_f32_16x16x32_bf16 v[66:69], v[240:243], v[224:227], v[66:69]
	s_barrier
	s_mov_b32 m0, s57
	ds_read_b128 v[172:175], v143 offset:49152
	ds_read_b128 v[176:179], v143 offset:50176
	ds_read_b128 v[180:183], v143 offset:51200
	ds_read_b128 v[184:187], v143 offset:52224
	ds_read_b128 v[188:191], v143 offset:53248
	ds_read_b128 v[192:195], v143 offset:54272
	ds_read_b128 v[196:199], v143 offset:55296
	ds_read_b128 v[224:227], v143 offset:56320
	global_load_lds_dwordx4 v134, s[78:79]
	s_mov_b32 m0, s58
	s_nop 0
	global_load_lds_dwordx4 v132, s[78:79]
	s_mov_b32 m0, s39
	s_nop 0
	global_load_lds_dwordx4 v0, s[76:77]
	s_add_i32 m0, s39, 0x2000
	s_add_u32 s48, s48, 0x80080
	s_addc_u32 s49, s49, 0
	global_load_lds_dwordx4 v130, s[76:77]
	s_add_i32 s39, s50, s52
	s_mov_b32 m0, s39
	s_nop 0
	global_load_lds_dwordx4 v0, s[48:49]
	s_add_i32 m0, s39, 0x2000
	s_nop 0
	global_load_lds_dwordx4 v130, s[48:49]
	s_waitcnt vmcnt(6) lgkmcnt(0)
	s_barrier
	v_mfma_f32_16x16x32_bf16 v[62:65], v[144:147], v[172:175], v[62:65]
	v_mfma_f32_16x16x32_bf16 v[58:61], v[152:155], v[172:175], v[58:61]
	v_mfma_f32_16x16x32_bf16 v[54:57], v[144:147], v[180:183], v[54:57]
	v_mfma_f32_16x16x32_bf16 v[50:53], v[152:155], v[180:183], v[50:53]
	v_mfma_f32_16x16x32_bf16 v[38:41], v[144:147], v[188:191], v[38:41]
	v_mfma_f32_16x16x32_bf16 v[34:37], v[152:155], v[188:191], v[34:37]
	v_mfma_f32_16x16x32_bf16 v[22:25], v[144:147], v[196:199], v[22:25]
	v_mfma_f32_16x16x32_bf16 v[18:21], v[152:155], v[196:199], v[18:21]
	v_mfma_f32_16x16x32_bf16 v[62:65], v[148:151], v[176:179], v[62:65]
	v_mfma_f32_16x16x32_bf16 v[58:61], v[168:171], v[176:179], v[58:61]
	v_mfma_f32_16x16x32_bf16 v[54:57], v[148:151], v[184:187], v[54:57]
	v_mfma_f32_16x16x32_bf16 v[50:53], v[168:171], v[184:187], v[50:53]
	v_mfma_f32_16x16x32_bf16 v[38:41], v[148:151], v[192:195], v[38:41]
	v_mfma_f32_16x16x32_bf16 v[34:37], v[168:171], v[192:195], v[34:37]
	v_mfma_f32_16x16x32_bf16 v[22:25], v[148:151], v[224:227], v[22:25]
	v_mfma_f32_16x16x32_bf16 v[18:21], v[168:171], v[224:227], v[18:21]
	v_mfma_f32_16x16x32_bf16 v[46:49], v[228:231], v[172:175], v[46:49]
	v_mfma_f32_16x16x32_bf16 v[42:45], v[236:239], v[172:175], v[42:45]
	v_mfma_f32_16x16x32_bf16 v[30:33], v[228:231], v[180:183], v[30:33]
	v_mfma_f32_16x16x32_bf16 v[26:29], v[236:239], v[180:183], v[26:29]
	v_mfma_f32_16x16x32_bf16 v[14:17], v[228:231], v[188:191], v[14:17]
	v_mfma_f32_16x16x32_bf16 v[10:13], v[236:239], v[188:191], v[10:13]
	v_mfma_f32_16x16x32_bf16 v[6:9], v[228:231], v[196:199], v[6:9]
	v_mfma_f32_16x16x32_bf16 v[2:5], v[236:239], v[196:199], v[2:5]
	v_mfma_f32_16x16x32_bf16 v[46:49], v[232:235], v[176:179], v[46:49]
	v_mfma_f32_16x16x32_bf16 v[42:45], v[240:243], v[176:179], v[42:45]
	v_mfma_f32_16x16x32_bf16 v[30:33], v[232:235], v[184:187], v[30:33]
	v_mfma_f32_16x16x32_bf16 v[26:29], v[240:243], v[184:187], v[26:29]
	v_mfma_f32_16x16x32_bf16 v[14:17], v[232:235], v[192:195], v[14:17]
	v_mfma_f32_16x16x32_bf16 v[10:13], v[240:243], v[192:195], v[10:13]
	v_mfma_f32_16x16x32_bf16 v[6:9], v[232:235], v[224:227], v[6:9]
	v_mfma_f32_16x16x32_bf16 v[2:5], v[240:243], v[224:227], v[2:5]
	s_barrier
	s_add_i32 s13, s13, 2
	s_add_u32 s46, s46, 0x100
	s_addc_u32 s47, s47, 0
	s_add_u32 s1, s1, 0x100
	s_addc_u32 s12, s12, 0
	s_cmp_gt_u32 s13, 29
	s_cbranch_scc0 .LBB0_234
	v_readlane_b32 s6, v255, 23
	v_lshl_add_u32 v150, s61, 8, v140
	v_lshl_or_b32 v144, s60, 8, v142
	v_readlane_b32 s7, v255, 24
	v_ashrrev_i32_e32 v145, 31, v144
	s_movk_i32 s1, 0x5800
	v_mov_b64_e32 v[146:147], s[6:7]
	v_cvt_pk_bf16_f32 v70, v70, v71
	v_cvt_pk_bf16_f32 v71, v72, v73
	v_cvt_pk_bf16_f32 v72, v66, v67
	v_add_u32_e32 v66, 0x80, v150
	v_mad_i64_i32 v[148:149], s[12:13], v150, s1, v[146:147]
	v_lshlrev_b64 v[144:145], 1, v[144:145]
	v_cvt_pk_bf16_f32 v110, v110, v111
	v_cvt_pk_bf16_f32 v111, v112, v113
	v_cvt_pk_bf16_f32 v112, v106, v107
	v_or_b32_e32 v106, 16, v150
	v_mad_i64_i32 v[66:67], s[12:13], v66, s1, v[146:147]
	v_cvt_pk_bf16_f32 v46, v46, v47
	v_cvt_pk_bf16_f32 v47, v48, v49
	v_cvt_pk_bf16_f32 v48, v42, v43
	v_add_u32_e32 v42, 0x90, v150
	v_lshl_add_u64 v[148:149], v[148:149], 0, v[144:145]
	v_cvt_pk_bf16_f32 v113, v108, v109
	v_mad_i64_i32 v[106:107], s[12:13], v106, s1, v[146:147]
	v_cvt_pk_bf16_f32 v94, v94, v95
	v_cvt_pk_bf16_f32 v95, v96, v97
	v_cvt_pk_bf16_f32 v96, v90, v91
	v_or_b32_e32 v90, 32, v150
	v_lshl_add_u64 v[66:67], v[66:67], 0, v[144:145]
	v_cvt_pk_bf16_f32 v49, v44, v45
	v_mad_i64_i32 v[42:43], s[12:13], v42, s1, v[146:147]
	v_cvt_pk_bf16_f32 v30, v30, v31
	v_cvt_pk_bf16_f32 v31, v32, v33
	v_cvt_pk_bf16_f32 v32, v26, v27
	v_add_u32_e32 v26, 0xa0, v150
	global_store_dwordx4 v[148:149], v[110:113], off offset:256
	v_cvt_pk_bf16_f32 v97, v92, v93
	v_mad_i64_i32 v[90:91], s[12:13], v90, s1, v[146:147]
	v_lshl_add_u64 v[110:111], v[106:107], 0, v[144:145]
	v_cvt_pk_bf16_f32 v78, v78, v79
	v_cvt_pk_bf16_f32 v79, v80, v81
	v_cvt_pk_bf16_f32 v80, v74, v75
	v_or_b32_e32 v74, 48, v150
	global_store_dwordx4 v[66:67], v[46:49], off offset:256
	v_cvt_pk_bf16_f32 v33, v28, v29
	v_mad_i64_i32 v[26:27], s[12:13], v26, s1, v[146:147]
	v_lshl_add_u64 v[46:47], v[42:43], 0, v[144:145]
	v_cvt_pk_bf16_f32 v14, v14, v15
	v_cvt_pk_bf16_f32 v15, v16, v17
	v_cvt_pk_bf16_f32 v16, v10, v11
	v_add_u32_e32 v10, 0xb0, v150
	global_store_dwordx4 v[110:111], v[94:97], off offset:256
	v_cvt_pk_bf16_f32 v81, v76, v77
	v_mad_i64_i32 v[74:75], s[12:13], v74, s1, v[146:147]
	v_lshl_add_u64 v[94:95], v[90:91], 0, v[144:145]
	global_store_dwordx4 v[46:47], v[30:33], off offset:256
	v_cvt_pk_bf16_f32 v17, v12, v13
	v_mad_i64_i32 v[10:11], s[12:13], v10, s1, v[146:147]
	v_lshl_add_u64 v[30:31], v[26:27], 0, v[144:145]
	v_cvt_pk_bf16_f32 v126, v126, v127
	v_cvt_pk_bf16_f32 v127, v128, v129
	v_cvt_pk_bf16_f32 v128, v122, v123
	v_cvt_pk_bf16_f32 v129, v124, v125
	v_cvt_pk_bf16_f32 v106, v118, v119
	v_cvt_pk_bf16_f32 v107, v120, v121
	v_cvt_pk_bf16_f32 v108, v114, v115
	v_cvt_pk_bf16_f32 v109, v116, v117
	v_cvt_pk_bf16_f32 v90, v102, v103
	v_cvt_pk_bf16_f32 v91, v104, v105
	v_cvt_pk_bf16_f32 v92, v98, v99
	v_cvt_pk_bf16_f32 v93, v100, v101
	global_store_dwordx4 v[94:95], v[78:81], off offset:256
	v_cvt_pk_bf16_f32 v76, v82, v83
	v_cvt_pk_bf16_f32 v77, v84, v85
	v_lshl_add_u64 v[78:79], v[74:75], 0, v[144:145]
	v_cvt_pk_bf16_f32 v74, v86, v87
	v_cvt_pk_bf16_f32 v75, v88, v89
	v_cvt_pk_bf16_f32 v73, v68, v69
	v_cvt_pk_bf16_f32 v62, v62, v63
	v_cvt_pk_bf16_f32 v63, v64, v65
	v_cvt_pk_bf16_f32 v64, v58, v59
	v_cvt_pk_bf16_f32 v65, v60, v61
	v_cvt_pk_bf16_f32 v42, v54, v55
	v_cvt_pk_bf16_f32 v43, v56, v57
	v_cvt_pk_bf16_f32 v44, v50, v51
	v_cvt_pk_bf16_f32 v45, v52, v53
	v_cvt_pk_bf16_f32 v26, v38, v39
	v_cvt_pk_bf16_f32 v27, v40, v41
	v_cvt_pk_bf16_f32 v28, v34, v35
	v_cvt_pk_bf16_f32 v29, v36, v37
	global_store_dwordx4 v[30:31], v[14:17], off offset:256
	v_cvt_pk_bf16_f32 v12, v18, v19
	v_cvt_pk_bf16_f32 v13, v20, v21
	v_lshl_add_u64 v[14:15], v[10:11], 0, v[144:145]
	v_cvt_pk_bf16_f32 v10, v22, v23
	v_cvt_pk_bf16_f32 v11, v24, v25
	v_cvt_pk_bf16_f32 v6, v6, v7
	v_cvt_pk_bf16_f32 v7, v8, v9
	v_cvt_pk_bf16_f32 v8, v2, v3
	v_cvt_pk_bf16_f32 v9, v4, v5
	s_and_b64 vcc, exec, s[40:41]
	s_mov_b32 s60, s0
	s_mov_b32 s61, s38
	s_mov_b64 s[48:49], s[44:45]
	s_mov_b64 s[46:47], s[42:43]
	global_store_dwordx4 v[148:149], v[126:129], off
	global_store_dwordx4 v[110:111], v[106:109], off
	global_store_dwordx4 v[94:95], v[90:93], off
	global_store_dwordx4 v[78:79], v[74:77], off
	global_store_dwordx4 v[78:79], v[70:73], off offset:256
	global_store_dwordx4 v[66:67], v[62:65], off
	global_store_dwordx4 v[46:47], v[42:45], off
	global_store_dwordx4 v[30:31], v[26:29], off
	global_store_dwordx4 v[14:15], v[10:13], off
	global_store_dwordx4 v[14:15], v[6:9], off offset:256
	s_cbranch_vccz .LBB0_227
	s_waitcnt vmcnt(0)
	v_readlane_b32 s60, v255, 21
	s_cmpk_gt_u32 s36, 0xff
	s_mov_b32 s18, s60
	v_readlane_b32 s61, v255, 22
	s_cbranch_scc1 .LBB0_238
	s_barrier

.LBB0_282:
	s_add_i32 s67, s50, 2
	s_add_u32 s51, s0, 0xfff80080
	s_addc_u32 s52, s1, -1
	s_add_i32 s68, 0, 0x10000
	ds_read_b128 v[136:139], v153
	ds_read_b128 v[140:143], v153 offset:1024
	ds_read_b128 v[144:147], v153 offset:2048
	ds_read_b128 v[148:151], v153 offset:3072
	s_cmp_eq_u32 s12, s50
	s_cselect_b32 s50, s48, s13
	s_cselect_b32 s53, s47, s52
	s_cselect_b32 s52, s46, s51
	s_cselect_b32 s51, s49, s66
	ds_read_b128 v[168:171], v155
	ds_read_b128 v[172:175], v155 offset:1024
	ds_read_b128 v[176:179], v155 offset:2048
	ds_read_b128 v[180:183], v155 offset:3072
	ds_read_b128 v[184:187], v155 offset:4096
	ds_read_b128 v[188:191], v155 offset:5120
	ds_read_b128 v[192:195], v155 offset:6144
	ds_read_b128 v[196:199], v155 offset:7168
	s_add_i32 m0, s55, 0xc000
	s_nop 0
	global_load_lds_dwordx4 v132, s[0:1]
	s_add_i32 m0, s55, 0xe000
	s_add_i32 s70, 0, 0x14000
	global_load_lds_dwordx4 v134, s[0:1]
	s_add_i32 s68, s68, s54
	ds_read_b128 v[224:227], v153 offset:16384
	ds_read_b128 v[228:231], v153 offset:17408
	ds_read_b128 v[232:235], v153 offset:18432
	ds_read_b128 v[236:239], v153 offset:19456
	s_waitcnt lgkmcnt(0)
	s_barrier
	v_mfma_f32_16x16x32_bf16 v[126:129], v[136:139], v[168:171], v[126:129]
	v_mfma_f32_16x16x32_bf16 v[122:125], v[144:147], v[168:171], v[122:125]
	v_mfma_f32_16x16x32_bf16 v[110:113], v[136:139], v[176:179], v[110:113]
	v_mfma_f32_16x16x32_bf16 v[106:109], v[144:147], v[176:179], v[106:109]
	v_mfma_f32_16x16x32_bf16 v[94:97], v[136:139], v[184:187], v[94:97]
	v_mfma_f32_16x16x32_bf16 v[90:93], v[144:147], v[184:187], v[90:93]
	v_mfma_f32_16x16x32_bf16 v[78:81], v[136:139], v[192:195], v[78:81]
	v_mfma_f32_16x16x32_bf16 v[74:77], v[144:147], v[192:195], v[74:77]
	v_mfma_f32_16x16x32_bf16 v[126:129], v[140:143], v[172:175], v[126:129]
	v_mfma_f32_16x16x32_bf16 v[122:125], v[148:151], v[172:175], v[122:125]
	v_mfma_f32_16x16x32_bf16 v[110:113], v[140:143], v[180:183], v[110:113]
	v_mfma_f32_16x16x32_bf16 v[106:109], v[148:151], v[180:183], v[106:109]
	v_mfma_f32_16x16x32_bf16 v[94:97], v[140:143], v[188:191], v[94:97]
	v_mfma_f32_16x16x32_bf16 v[90:93], v[148:151], v[188:191], v[90:93]
	v_mfma_f32_16x16x32_bf16 v[78:81], v[140:143], v[196:199], v[78:81]
	v_mfma_f32_16x16x32_bf16 v[74:77], v[148:151], v[196:199], v[74:77]
	v_mfma_f32_16x16x32_bf16 v[118:121], v[224:227], v[168:171], v[118:121]
	v_mfma_f32_16x16x32_bf16 v[114:117], v[232:235], v[168:171], v[114:117]
	v_mfma_f32_16x16x32_bf16 v[102:105], v[224:227], v[176:179], v[102:105]
	v_mfma_f32_16x16x32_bf16 v[98:101], v[232:235], v[176:179], v[98:101]
	v_mfma_f32_16x16x32_bf16 v[86:89], v[224:227], v[184:187], v[86:89]
	v_mfma_f32_16x16x32_bf16 v[82:85], v[232:235], v[184:187], v[82:85]
	v_mfma_f32_16x16x32_bf16 v[70:73], v[224:227], v[192:195], v[70:73]
	v_mfma_f32_16x16x32_bf16 v[66:69], v[232:235], v[192:195], v[66:69]
	v_mfma_f32_16x16x32_bf16 v[118:121], v[228:231], v[172:175], v[118:121]
	v_mfma_f32_16x16x32_bf16 v[114:117], v[236:239], v[172:175], v[114:117]
	v_mfma_f32_16x16x32_bf16 v[102:105], v[228:231], v[180:183], v[102:105]
	v_mfma_f32_16x16x32_bf16 v[98:101], v[236:239], v[180:183], v[98:101]
	v_mfma_f32_16x16x32_bf16 v[86:89], v[228:231], v[188:191], v[86:89]
	v_mfma_f32_16x16x32_bf16 v[82:85], v[236:239], v[188:191], v[82:85]
	v_mfma_f32_16x16x32_bf16 v[70:73], v[228:231], v[196:199], v[70:73]
	v_mfma_f32_16x16x32_bf16 v[66:69], v[236:239], v[196:199], v[66:69]
	s_barrier
	s_mov_b32 m0, s55
	s_add_u32 s78, s52, s94
	s_addc_u32 s79, s53, s95
	ds_read_b128 v[168:171], v155 offset:16384
	ds_read_b128 v[172:175], v155 offset:17408
	ds_read_b128 v[176:179], v155 offset:18432
	ds_read_b128 v[180:183], v155 offset:19456
	ds_read_b128 v[184:187], v155 offset:20480
	ds_read_b128 v[188:191], v155 offset:21504
	ds_read_b128 v[192:195], v155 offset:22528
	ds_read_b128 v[196:199], v155 offset:23552
	global_load_lds_dwordx4 v0, s[52:53]
	s_mov_b32 m0, s56
	s_add_u32 s76, s50, s94
	s_addc_u32 s77, s51, s95
	global_load_lds_dwordx4 v130, s[52:53]
	s_mov_b32 m0, s68
	s_nop 0
	global_load_lds_dwordx4 v0, s[50:51]
	s_add_i32 m0, s68, 0x2000
	s_add_u32 s68, s50, 0x80000
	s_addc_u32 s69, s51, 0
	global_load_lds_dwordx4 v130, s[50:51]
	s_add_i32 s70, s70, s54
	s_mov_b32 m0, s70
	s_nop 0
	global_load_lds_dwordx4 v0, s[68:69]
	s_add_i32 m0, s70, 0x2000
	s_nop 0
	global_load_lds_dwordx4 v130, s[68:69]
	s_waitcnt vmcnt(6) lgkmcnt(0)
	s_barrier
	v_mfma_f32_16x16x32_bf16 v[62:65], v[136:139], v[168:171], v[62:65]
	v_mfma_f32_16x16x32_bf16 v[58:61], v[144:147], v[168:171], v[58:61]
	v_mfma_f32_16x16x32_bf16 v[46:49], v[136:139], v[176:179], v[46:49]
	v_mfma_f32_16x16x32_bf16 v[42:45], v[144:147], v[176:179], v[42:45]
	v_mfma_f32_16x16x32_bf16 v[30:33], v[136:139], v[184:187], v[30:33]
	v_mfma_f32_16x16x32_bf16 v[26:29], v[144:147], v[184:187], v[26:29]
	v_mfma_f32_16x16x32_bf16 v[14:17], v[136:139], v[192:195], v[14:17]
	v_mfma_f32_16x16x32_bf16 v[10:13], v[144:147], v[192:195], v[10:13]
	v_mfma_f32_16x16x32_bf16 v[62:65], v[140:143], v[172:175], v[62:65]
	v_mfma_f32_16x16x32_bf16 v[58:61], v[148:151], v[172:175], v[58:61]
	v_mfma_f32_16x16x32_bf16 v[46:49], v[140:143], v[180:183], v[46:49]
	v_mfma_f32_16x16x32_bf16 v[42:45], v[148:151], v[180:183], v[42:45]
	v_mfma_f32_16x16x32_bf16 v[30:33], v[140:143], v[188:191], v[30:33]
	v_mfma_f32_16x16x32_bf16 v[26:29], v[148:151], v[188:191], v[26:29]
	v_mfma_f32_16x16x32_bf16 v[14:17], v[140:143], v[196:199], v[14:17]
	v_mfma_f32_16x16x32_bf16 v[10:13], v[148:151], v[196:199], v[10:13]
	v_mfma_f32_16x16x32_bf16 v[54:57], v[224:227], v[168:171], v[54:57]
	v_mfma_f32_16x16x32_bf16 v[50:53], v[232:235], v[168:171], v[50:53]
	v_mfma_f32_16x16x32_bf16 v[38:41], v[224:227], v[176:179], v[38:41]
	v_mfma_f32_16x16x32_bf16 v[34:37], v[232:235], v[176:179], v[34:37]
	v_mfma_f32_16x16x32_bf16 v[22:25], v[224:227], v[184:187], v[22:25]
	v_mfma_f32_16x16x32_bf16 v[18:21], v[232:235], v[184:187], v[18:21]
	v_mfma_f32_16x16x32_bf16 v[6:9], v[224:227], v[192:195], v[6:9]
	v_mfma_f32_16x16x32_bf16 v[2:5], v[232:235], v[192:195], v[2:5]
	v_mfma_f32_16x16x32_bf16 v[54:57], v[228:231], v[172:175], v[54:57]
	v_mfma_f32_16x16x32_bf16 v[50:53], v[236:239], v[172:175], v[50:53]
	v_mfma_f32_16x16x32_bf16 v[38:41], v[228:231], v[180:183], v[38:41]
	v_mfma_f32_16x16x32_bf16 v[34:37], v[236:239], v[180:183], v[34:37]
	v_mfma_f32_16x16x32_bf16 v[22:25], v[228:231], v[188:191], v[22:25]
	v_mfma_f32_16x16x32_bf16 v[18:21], v[236:239], v[188:191], v[18:21]
	v_mfma_f32_16x16x32_bf16 v[6:9], v[228:231], v[196:199], v[6:9]
	v_mfma_f32_16x16x32_bf16 v[2:5], v[236:239], v[196:199], v[2:5]
	s_barrier
	s_add_i32 s68, 0, 0x18000
	ds_read_b128 v[136:139], v153 offset:32768
	ds_read_b128 v[140:143], v153 offset:33792
	ds_read_b128 v[144:147], v153 offset:34816
	ds_read_b128 v[148:151], v153 offset:35840
	s_add_u32 s52, s52, 0x80000
	s_addc_u32 s53, s53, 0
	ds_read_b128 v[168:171], v155 offset:32768
	ds_read_b128 v[172:175], v155 offset:33792
	ds_read_b128 v[176:179], v155 offset:34816
	ds_read_b128 v[180:183], v155 offset:35840
	ds_read_b128 v[184:187], v155 offset:36864
	ds_read_b128 v[188:191], v155 offset:37888
	ds_read_b128 v[192:195], v155 offset:38912
	ds_read_b128 v[196:199], v155 offset:39936
	s_mov_b32 m0, s57
	s_nop 0
	global_load_lds_dwordx4 v0, s[52:53]
	s_mov_b32 m0, s58
	s_nop 0
	global_load_lds_dwordx4 v130, s[52:53]
	s_add_i32 s52, 0, 0x1c000
	s_add_i32 s53, s68, s54
	ds_read_b128 v[224:227], v153 offset:49152
	ds_read_b128 v[228:231], v153 offset:50176
	ds_read_b128 v[232:235], v153 offset:51200
	ds_read_b128 v[236:239], v153 offset:52224
	s_waitcnt lgkmcnt(0)
	s_barrier
	v_mfma_f32_16x16x32_bf16 v[126:129], v[136:139], v[168:171], v[126:129]
	v_mfma_f32_16x16x32_bf16 v[122:125], v[144:147], v[168:171], v[122:125]
	v_mfma_f32_16x16x32_bf16 v[110:113], v[136:139], v[176:179], v[110:113]
	v_mfma_f32_16x16x32_bf16 v[106:109], v[144:147], v[176:179], v[106:109]
	v_mfma_f32_16x16x32_bf16 v[94:97], v[136:139], v[184:187], v[94:97]
	v_mfma_f32_16x16x32_bf16 v[90:93], v[144:147], v[184:187], v[90:93]
	v_mfma_f32_16x16x32_bf16 v[78:81], v[136:139], v[192:195], v[78:81]
	v_mfma_f32_16x16x32_bf16 v[74:77], v[144:147], v[192:195], v[74:77]
	v_mfma_f32_16x16x32_bf16 v[126:129], v[140:143], v[172:175], v[126:129]
	v_mfma_f32_16x16x32_bf16 v[122:125], v[148:151], v[172:175], v[122:125]
	v_mfma_f32_16x16x32_bf16 v[110:113], v[140:143], v[180:183], v[110:113]
	v_mfma_f32_16x16x32_bf16 v[106:109], v[148:151], v[180:183], v[106:109]
	v_mfma_f32_16x16x32_bf16 v[94:97], v[140:143], v[188:191], v[94:97]
	v_mfma_f32_16x16x32_bf16 v[90:93], v[148:151], v[188:191], v[90:93]
	v_mfma_f32_16x16x32_bf16 v[78:81], v[140:143], v[196:199], v[78:81]
	v_mfma_f32_16x16x32_bf16 v[74:77], v[148:151], v[196:199], v[74:77]
	v_mfma_f32_16x16x32_bf16 v[118:121], v[224:227], v[168:171], v[118:121]
	v_mfma_f32_16x16x32_bf16 v[114:117], v[232:235], v[168:171], v[114:117]
	v_mfma_f32_16x16x32_bf16 v[102:105], v[224:227], v[176:179], v[102:105]
	v_mfma_f32_16x16x32_bf16 v[98:101], v[232:235], v[176:179], v[98:101]
	v_mfma_f32_16x16x32_bf16 v[86:89], v[224:227], v[184:187], v[86:89]
	v_mfma_f32_16x16x32_bf16 v[82:85], v[232:235], v[184:187], v[82:85]
	v_mfma_f32_16x16x32_bf16 v[70:73], v[224:227], v[192:195], v[70:73]
	v_mfma_f32_16x16x32_bf16 v[66:69], v[232:235], v[192:195], v[66:69]
	v_mfma_f32_16x16x32_bf16 v[118:121], v[228:231], v[172:175], v[118:121]
	v_mfma_f32_16x16x32_bf16 v[114:117], v[236:239], v[172:175], v[114:117]
	v_mfma_f32_16x16x32_bf16 v[102:105], v[228:231], v[180:183], v[102:105]
	v_mfma_f32_16x16x32_bf16 v[98:101], v[236:239], v[180:183], v[98:101]
	v_mfma_f32_16x16x32_bf16 v[86:89], v[228:231], v[188:191], v[86:89]
	v_mfma_f32_16x16x32_bf16 v[82:85], v[236:239], v[188:191], v[82:85]
	v_mfma_f32_16x16x32_bf16 v[70:73], v[228:231], v[196:199], v[70:73]
	v_mfma_f32_16x16x32_bf16 v[66:69], v[236:239], v[196:199], v[66:69]
	s_barrier
	s_mov_b32 m0, s59
	ds_read_b128 v[168:171], v155 offset:49152
	ds_read_b128 v[172:175], v155 offset:50176
	ds_read_b128 v[176:179], v155 offset:51200
	ds_read_b128 v[180:183], v155 offset:52224
	ds_read_b128 v[184:187], v155 offset:53248
	ds_read_b128 v[188:191], v155 offset:54272
	ds_read_b128 v[192:195], v155 offset:55296
	ds_read_b128 v[196:199], v155 offset:56320
	global_load_lds_dwordx4 v0, s[78:79]
	s_mov_b32 m0, s60
	s_nop 0
	global_load_lds_dwordx4 v130, s[78:79]
	s_mov_b32 m0, s53
	s_nop 0
	global_load_lds_dwordx4 v0, s[76:77]
	s_add_i32 m0, s53, 0x2000
	s_add_u32 s50, s50, 0x80080
	s_addc_u32 s51, s51, 0
	global_load_lds_dwordx4 v130, s[76:77]
	s_add_i32 s52, s52, s54
	s_mov_b32 m0, s52
	s_nop 0
	global_load_lds_dwordx4 v0, s[50:51]
	s_add_i32 m0, s52, 0x2000
	s_nop 0
	global_load_lds_dwordx4 v130, s[50:51]
	s_waitcnt vmcnt(6) lgkmcnt(0)
	s_barrier
	v_mfma_f32_16x16x32_bf16 v[62:65], v[136:139], v[168:171], v[62:65]
	v_mfma_f32_16x16x32_bf16 v[58:61], v[144:147], v[168:171], v[58:61]
	v_mfma_f32_16x16x32_bf16 v[46:49], v[136:139], v[176:179], v[46:49]
	v_mfma_f32_16x16x32_bf16 v[42:45], v[144:147], v[176:179], v[42:45]
	v_mfma_f32_16x16x32_bf16 v[30:33], v[136:139], v[184:187], v[30:33]
	v_mfma_f32_16x16x32_bf16 v[26:29], v[144:147], v[184:187], v[26:29]
	v_mfma_f32_16x16x32_bf16 v[14:17], v[136:139], v[192:195], v[14:17]
	v_mfma_f32_16x16x32_bf16 v[10:13], v[144:147], v[192:195], v[10:13]
	v_mfma_f32_16x16x32_bf16 v[62:65], v[140:143], v[172:175], v[62:65]
	v_mfma_f32_16x16x32_bf16 v[58:61], v[148:151], v[172:175], v[58:61]
	v_mfma_f32_16x16x32_bf16 v[46:49], v[140:143], v[180:183], v[46:49]
	v_mfma_f32_16x16x32_bf16 v[42:45], v[148:151], v[180:183], v[42:45]
	v_mfma_f32_16x16x32_bf16 v[30:33], v[140:143], v[188:191], v[30:33]
	v_mfma_f32_16x16x32_bf16 v[26:29], v[148:151], v[188:191], v[26:29]
	v_mfma_f32_16x16x32_bf16 v[14:17], v[140:143], v[196:199], v[14:17]
	v_mfma_f32_16x16x32_bf16 v[10:13], v[148:151], v[196:199], v[10:13]
	v_mfma_f32_16x16x32_bf16 v[54:57], v[224:227], v[168:171], v[54:57]
	v_mfma_f32_16x16x32_bf16 v[50:53], v[232:235], v[168:171], v[50:53]
	v_mfma_f32_16x16x32_bf16 v[38:41], v[224:227], v[176:179], v[38:41]
	v_mfma_f32_16x16x32_bf16 v[34:37], v[232:235], v[176:179], v[34:37]
	v_mfma_f32_16x16x32_bf16 v[22:25], v[224:227], v[184:187], v[22:25]
	v_mfma_f32_16x16x32_bf16 v[18:21], v[232:235], v[184:187], v[18:21]
	v_mfma_f32_16x16x32_bf16 v[6:9], v[224:227], v[192:195], v[6:9]
	v_mfma_f32_16x16x32_bf16 v[2:5], v[232:235], v[192:195], v[2:5]
	v_mfma_f32_16x16x32_bf16 v[54:57], v[228:231], v[172:175], v[54:57]
	v_mfma_f32_16x16x32_bf16 v[50:53], v[236:239], v[172:175], v[50:53]
	v_mfma_f32_16x16x32_bf16 v[38:41], v[228:231], v[180:183], v[38:41]
	v_mfma_f32_16x16x32_bf16 v[34:37], v[236:239], v[180:183], v[34:37]
	v_mfma_f32_16x16x32_bf16 v[22:25], v[228:231], v[188:191], v[22:25]
	v_mfma_f32_16x16x32_bf16 v[18:21], v[236:239], v[188:191], v[18:21]
	v_mfma_f32_16x16x32_bf16 v[6:9], v[228:231], v[196:199], v[6:9]
	v_mfma_f32_16x16x32_bf16 v[2:5], v[236:239], v[196:199], v[2:5]
	s_barrier
	s_add_u32 s0, s0, 0x100
	s_addc_u32 s1, s1, 0
	s_add_u32 s13, s13, 0x100
	s_addc_u32 s66, s66, 0
	s_mov_b32 s50, s67
	s_cmp_ge_i32 s67, s41
	s_cbranch_scc0 .LBB0_282
	s_cmp_eq_u32 s63, 2
	s_cbranch_scc1 .Lepi6_orig
	v_readlane_b32 s90, v255, 17
	v_readlane_b32 s91, v255, 18
	v_readlane_b32 s96, v255, 19
	v_readlane_b32 s97, v255, 20
	v_readlane_b32 s8, v255, 25
	v_readlane_b32 s9, v255, 26
	v_readlane_b32 s68, v253, 58
	v_readlane_b32 s69, v253, 59
	v_lshl_or_b32 v156, s64, 8, v154
	v_lshlrev_b32_e32 v156, 2, v156
	v_lshl_add_u32 v157, v152, 13, v156
	s_lshl_b32 s72, s65, 21
	s_add_u32 s74, s68, s72
	s_addc_u32 s75, s69, 0
	s_add_u32 s76, s22, s72
	s_addc_u32 s77, s23, 0
	s_lshr_b32 s73, s65, 3
	s_mul_i32 s73, s73, 0xc000
	s_add_u32 s73, s73, 0x4000
	s_add_u32 s70, s90, s73
	s_addc_u32 s71, s91, 0
	global_load_dwordx4 v[140:143], v156, s[70:71]
	global_load_dwordx4 v[144:147], v156, s[70:71] offset:64
	global_load_dwordx4 v[148:151], v156, s[70:71] offset:512
	global_load_dwordx4 v[168:171], v156, s[70:71] offset:576
	global_load_dwordx4 v[224:227], v157, s[74:75] nt
	global_load_dwordx4 v[228:231], v157, s[74:75] offset:64 nt
	global_load_dwordx4 v[232:235], v157, s[74:75] offset:512 nt
	global_load_dwordx4 v[236:239], v157, s[74:75] offset:576 nt
	s_add_u32 s74, s74, 0x20000
	s_addc_u32 s75, s75, 0
	global_load_dwordx4 v[240:243], v157, s[74:75] nt
	global_load_dwordx4 v[244:247], v157, s[74:75] offset:64 nt
	s_waitcnt vmcnt(5)
	v_pk_fma_f32 v[128:129], v[128:129], v[142:143], v[226:227]
	v_pk_fma_f32 v[126:127], v[126:127], v[140:141], v[224:225]
	global_store_dwordx4 v157, v[126:129], s[76:77]
	global_load_dwordx4 v[224:227], v157, s[74:75] offset:512 nt
	s_waitcnt vmcnt(6)
	v_pk_fma_f32 v[124:125], v[124:125], v[146:147], v[230:231]
	v_pk_fma_f32 v[122:123], v[122:123], v[144:145], v[228:229]
	global_store_dwordx4 v157, v[122:125], s[76:77] offset:64
	global_load_dwordx4 v[228:231], v157, s[74:75] offset:576 nt
	s_waitcnt vmcnt(7)
	v_pk_fma_f32 v[120:121], v[120:121], v[150:151], v[234:235]
	v_pk_fma_f32 v[118:119], v[118:119], v[148:149], v[232:233]
	global_store_dwordx4 v157, v[118:121], s[76:77] offset:512
	s_add_u32 s74, s74, 0x20000
	s_addc_u32 s75, s75, 0
	global_load_dwordx4 v[232:235], v157, s[74:75] nt
	s_waitcnt vmcnt(8)
	v_pk_fma_f32 v[116:117], v[116:117], v[170:171], v[238:239]
	v_pk_fma_f32 v[114:115], v[114:115], v[168:169], v[236:237]
	global_store_dwordx4 v157, v[114:117], s[76:77] offset:576
	global_load_dwordx4 v[236:239], v157, s[74:75] offset:64 nt
	s_add_u32 s76, s76, 0x20000
	s_addc_u32 s77, s77, 0
	s_waitcnt vmcnt(9)
	v_pk_fma_f32 v[112:113], v[112:113], v[142:143], v[242:243]
	v_pk_fma_f32 v[110:111], v[110:111], v[140:141], v[240:241]
	global_store_dwordx4 v157, v[110:113], s[76:77]
	global_load_dwordx4 v[240:243], v157, s[74:75] offset:512 nt
	s_waitcnt vmcnt(10)
	v_pk_fma_f32 v[108:109], v[108:109], v[146:147], v[246:247]
	v_pk_fma_f32 v[106:107], v[106:107], v[144:145], v[244:245]
	global_store_dwordx4 v157, v[106:109], s[76:77] offset:64
	global_load_dwordx4 v[244:247], v157, s[74:75] offset:576 nt
	s_waitcnt vmcnt(10)
	v_pk_fma_f32 v[104:105], v[104:105], v[150:151], v[226:227]
	v_pk_fma_f32 v[102:103], v[102:103], v[148:149], v[224:225]
	global_store_dwordx4 v157, v[102:105], s[76:77] offset:512
	s_add_u32 s74, s74, 0x20000
	s_addc_u32 s75, s75, 0
	global_load_dwordx4 v[224:227], v157, s[74:75] nt
	s_waitcnt vmcnt(10)
	v_pk_fma_f32 v[100:101], v[100:101], v[170:171], v[230:231]
	v_pk_fma_f32 v[98:99], v[98:99], v[168:169], v[228:229]
	global_store_dwordx4 v157, v[98:101], s[76:77] offset:576
	global_load_dwordx4 v[228:231], v157, s[74:75] offset:64 nt
	s_add_u32 s76, s76, 0x20000
	s_addc_u32 s77, s77, 0
	s_waitcnt vmcnt(10)
	v_pk_fma_f32 v[96:97], v[96:97], v[142:143], v[234:235]
	v_pk_fma_f32 v[94:95], v[94:95], v[140:141], v[232:233]
	global_store_dwordx4 v157, v[94:97], s[76:77]
	global_load_dwordx4 v[232:235], v157, s[74:75] offset:512 nt
	s_waitcnt vmcnt(10)
	v_pk_fma_f32 v[92:93], v[92:93], v[146:147], v[238:239]
	v_pk_fma_f32 v[90:91], v[90:91], v[144:145], v[236:237]
	global_store_dwordx4 v157, v[90:93], s[76:77] offset:64
	global_load_dwordx4 v[236:239], v157, s[74:75] offset:576 nt
	s_waitcnt vmcnt(10)
	v_pk_fma_f32 v[88:89], v[88:89], v[150:151], v[242:243]
	v_pk_fma_f32 v[86:87], v[86:87], v[148:149], v[240:241]
	global_store_dwordx4 v157, v[86:89], s[76:77] offset:512
	s_add_u32 s74, s74, 0xa0000
	s_addc_u32 s75, s75, 0
	global_load_dwordx4 v[240:243], v157, s[74:75] nt
	s_waitcnt vmcnt(10)
	v_pk_fma_f32 v[84:85], v[84:85], v[170:171], v[246:247]
	v_pk_fma_f32 v[82:83], v[82:83], v[168:169], v[244:245]
	global_store_dwordx4 v157, v[82:85], s[76:77] offset:576
	global_load_dwordx4 v[244:247], v157, s[74:75] offset:64 nt
	s_add_u32 s76, s76, 0x20000
	s_addc_u32 s77, s77, 0
	s_waitcnt vmcnt(10)
	v_pk_fma_f32 v[80:81], v[80:81], v[142:143], v[226:227]
	v_pk_fma_f32 v[78:79], v[78:79], v[140:141], v[224:225]
	global_store_dwordx4 v157, v[78:81], s[76:77]
	global_load_dwordx4 v[224:227], v157, s[74:75] offset:512 nt
	s_waitcnt vmcnt(10)
	v_pk_fma_f32 v[76:77], v[76:77], v[146:147], v[230:231]
	v_pk_fma_f32 v[74:75], v[74:75], v[144:145], v[228:229]
	global_store_dwordx4 v157, v[74:77], s[76:77] offset:64
	global_load_dwordx4 v[228:231], v157, s[74:75] offset:576 nt
	s_waitcnt vmcnt(10)
	v_pk_fma_f32 v[72:73], v[72:73], v[150:151], v[234:235]
	v_pk_fma_f32 v[70:71], v[70:71], v[148:149], v[232:233]
	global_store_dwordx4 v157, v[70:73], s[76:77] offset:512
	s_add_u32 s74, s74, 0x20000
	s_addc_u32 s75, s75, 0
	global_load_dwordx4 v[232:235], v157, s[74:75] nt
	s_waitcnt vmcnt(10)
	v_pk_fma_f32 v[68:69], v[68:69], v[170:171], v[238:239]
	v_pk_fma_f32 v[66:67], v[66:67], v[168:169], v[236:237]
	global_store_dwordx4 v157, v[66:69], s[76:77] offset:576
	global_load_dwordx4 v[236:239], v157, s[74:75] offset:64 nt
	s_add_u32 s76, s76, 0xa0000
	s_addc_u32 s77, s77, 0
	s_waitcnt vmcnt(10)
	v_pk_fma_f32 v[64:65], v[64:65], v[142:143], v[242:243]
	v_pk_fma_f32 v[62:63], v[62:63], v[140:141], v[240:241]
	global_store_dwordx4 v157, v[62:65], s[76:77]
	global_load_dwordx4 v[240:243], v157, s[74:75] offset:512 nt
	s_waitcnt vmcnt(10)
	v_pk_fma_f32 v[60:61], v[60:61], v[146:147], v[246:247]
	v_pk_fma_f32 v[58:59], v[58:59], v[144:145], v[244:245]
	global_store_dwordx4 v157, v[58:61], s[76:77] offset:64
	global_load_dwordx4 v[244:247], v157, s[74:75] offset:576 nt
	s_waitcnt vmcnt(10)
	v_pk_fma_f32 v[56:57], v[56:57], v[150:151], v[226:227]
	v_pk_fma_f32 v[54:55], v[54:55], v[148:149], v[224:225]
	global_store_dwordx4 v157, v[54:57], s[76:77] offset:512
	s_add_u32 s74, s74, 0x20000
	s_addc_u32 s75, s75, 0
	global_load_dwordx4 v[224:227], v157, s[74:75] nt
	s_waitcnt vmcnt(10)
	v_pk_fma_f32 v[52:53], v[52:53], v[170:171], v[230:231]
	v_pk_fma_f32 v[50:51], v[50:51], v[168:169], v[228:229]
	global_store_dwordx4 v157, v[50:53], s[76:77] offset:576
	global_load_dwordx4 v[228:231], v157, s[74:75] offset:64 nt
	s_add_u32 s76, s76, 0x20000
	s_addc_u32 s77, s77, 0
	s_waitcnt vmcnt(10)
	v_pk_fma_f32 v[48:49], v[48:49], v[142:143], v[234:235]
	v_pk_fma_f32 v[46:47], v[46:47], v[140:141], v[232:233]
	global_store_dwordx4 v157, v[46:49], s[76:77]
	global_load_dwordx4 v[232:235], v157, s[74:75] offset:512 nt
	s_waitcnt vmcnt(10)
	v_pk_fma_f32 v[44:45], v[44:45], v[146:147], v[238:239]
	v_pk_fma_f32 v[42:43], v[42:43], v[144:145], v[236:237]
	global_store_dwordx4 v157, v[42:45], s[76:77] offset:64
	global_load_dwordx4 v[236:239], v157, s[74:75] offset:576 nt
	s_waitcnt vmcnt(10)
	v_pk_fma_f32 v[40:41], v[40:41], v[150:151], v[242:243]
	v_pk_fma_f32 v[38:39], v[38:39], v[148:149], v[240:241]
	global_store_dwordx4 v157, v[38:41], s[76:77] offset:512
	s_add_u32 s74, s74, 0x20000
	s_addc_u32 s75, s75, 0
	global_load_dwordx4 v[240:243], v157, s[74:75] nt
	s_waitcnt vmcnt(10)
	v_pk_fma_f32 v[36:37], v[36:37], v[170:171], v[246:247]
	v_pk_fma_f32 v[34:35], v[34:35], v[168:169], v[244:245]
	global_store_dwordx4 v157, v[34:37], s[76:77] offset:576
	global_load_dwordx4 v[244:247], v157, s[74:75] offset:64 nt
	s_add_u32 s76, s76, 0x20000
	s_addc_u32 s77, s77, 0
	s_waitcnt vmcnt(10)
	v_pk_fma_f32 v[32:33], v[32:33], v[142:143], v[226:227]
	v_pk_fma_f32 v[30:31], v[30:31], v[140:141], v[224:225]
	global_store_dwordx4 v157, v[30:33], s[76:77]
	global_load_dwordx4 v[224:227], v157, s[74:75] offset:512 nt
	s_waitcnt vmcnt(10)
	v_pk_fma_f32 v[28:29], v[28:29], v[146:147], v[230:231]
	v_pk_fma_f32 v[26:27], v[26:27], v[144:145], v[228:229]
	global_store_dwordx4 v157, v[26:29], s[76:77] offset:64
	global_load_dwordx4 v[228:231], v157, s[74:75] offset:576 nt
	s_waitcnt vmcnt(10)
	v_pk_fma_f32 v[24:25], v[24:25], v[150:151], v[234:235]
	v_pk_fma_f32 v[22:23], v[22:23], v[148:149], v[232:233]
	global_store_dwordx4 v157, v[22:25], s[76:77] offset:512
	s_waitcnt vmcnt(9)
	v_pk_fma_f32 v[20:21], v[20:21], v[170:171], v[238:239]
	v_pk_fma_f32 v[18:19], v[18:19], v[168:169], v[236:237]
	global_store_dwordx4 v157, v[18:21], s[76:77] offset:576
	s_add_u32 s76, s76, 0x20000
	s_addc_u32 s77, s77, 0
	s_waitcnt vmcnt(8)
	v_pk_fma_f32 v[16:17], v[16:17], v[142:143], v[242:243]
	v_pk_fma_f32 v[14:15], v[14:15], v[140:141], v[240:241]
	global_store_dwordx4 v157, v[14:17], s[76:77]
	s_waitcnt vmcnt(7)
	v_pk_fma_f32 v[12:13], v[12:13], v[146:147], v[246:247]
	v_pk_fma_f32 v[10:11], v[10:11], v[144:145], v[244:245]
	global_store_dwordx4 v157, v[10:13], s[76:77] offset:64
	s_waitcnt vmcnt(6)
	v_pk_fma_f32 v[8:9], v[8:9], v[150:151], v[226:227]
	v_pk_fma_f32 v[6:7], v[6:7], v[148:149], v[224:225]
	global_store_dwordx4 v157, v[6:9], s[76:77] offset:512
	s_waitcnt vmcnt(5)
	v_pk_fma_f32 v[4:5], v[4:5], v[170:171], v[230:231]
	v_pk_fma_f32 v[2:3], v[2:3], v[168:169], v[228:229]
	global_store_dwordx4 v157, v[2:5], s[76:77] offset:576
	s_branch .LBB0_269

.LBB0_572:
	s_add_u32 s41, s46, 0xfff80080
	s_addc_u32 s48, s47, -1
	s_add_i32 s64, 0, 0x10000
	ds_read_b128 v[144:147], v141
	ds_read_b128 v[148:151], v141 offset:1024
	ds_read_b128 v[152:155], v141 offset:2048
	ds_read_b128 v[168:171], v141 offset:3072
	s_cmp_eq_u32 s39, 28
	s_cselect_b32 s51, s43, s48
	s_cselect_b32 s50, s42, s41
	s_cselect_b32 s49, s45, s13
	s_cselect_b32 s48, s44, s12
	ds_read_b128 v[172:175], v143
	ds_read_b128 v[176:179], v143 offset:1024
	ds_read_b128 v[180:183], v143 offset:2048
	ds_read_b128 v[184:187], v143 offset:3072
	ds_read_b128 v[188:191], v143 offset:4096
	ds_read_b128 v[192:195], v143 offset:5120
	ds_read_b128 v[196:199], v143 offset:6144
	ds_read_b128 v[224:227], v143 offset:7168
	s_add_i32 m0, s54, 0xc000
	s_nop 0
	global_load_lds_dwordx4 v136, s[46:47]
	s_add_i32 m0, s54, 0xe000
	s_add_i32 s41, 0, 0x14000
	global_load_lds_dwordx4 v138, s[46:47]
	s_add_i32 s64, s64, s53
	ds_read_b128 v[228:231], v141 offset:16384
	ds_read_b128 v[232:235], v141 offset:17408
	ds_read_b128 v[236:239], v141 offset:18432
	ds_read_b128 v[240:243], v141 offset:19456
	s_waitcnt lgkmcnt(0)
	s_barrier
	v_mfma_f32_16x16x32_bf16 v[126:129], v[144:147], v[172:175], v[126:129]
	v_mfma_f32_16x16x32_bf16 v[122:125], v[152:155], v[172:175], v[122:125]
	v_mfma_f32_16x16x32_bf16 v[118:121], v[144:147], v[180:183], v[118:121]
	v_mfma_f32_16x16x32_bf16 v[114:117], v[152:155], v[180:183], v[114:117]
	v_mfma_f32_16x16x32_bf16 v[102:105], v[144:147], v[188:191], v[102:105]
	v_mfma_f32_16x16x32_bf16 v[98:101], v[152:155], v[188:191], v[98:101]
	v_mfma_f32_16x16x32_bf16 v[86:89], v[144:147], v[196:199], v[86:89]
	v_mfma_f32_16x16x32_bf16 v[82:85], v[152:155], v[196:199], v[82:85]
	v_mfma_f32_16x16x32_bf16 v[126:129], v[148:151], v[176:179], v[126:129]
	v_mfma_f32_16x16x32_bf16 v[122:125], v[168:171], v[176:179], v[122:125]
	v_mfma_f32_16x16x32_bf16 v[118:121], v[148:151], v[184:187], v[118:121]
	v_mfma_f32_16x16x32_bf16 v[114:117], v[168:171], v[184:187], v[114:117]
	v_mfma_f32_16x16x32_bf16 v[102:105], v[148:151], v[192:195], v[102:105]
	v_mfma_f32_16x16x32_bf16 v[98:101], v[168:171], v[192:195], v[98:101]
	v_mfma_f32_16x16x32_bf16 v[86:89], v[148:151], v[224:227], v[86:89]
	v_mfma_f32_16x16x32_bf16 v[82:85], v[168:171], v[224:227], v[82:85]
	v_mfma_f32_16x16x32_bf16 v[110:113], v[228:231], v[172:175], v[110:113]
	v_mfma_f32_16x16x32_bf16 v[106:109], v[236:239], v[172:175], v[106:109]
	v_mfma_f32_16x16x32_bf16 v[94:97], v[228:231], v[180:183], v[94:97]
	v_mfma_f32_16x16x32_bf16 v[90:93], v[236:239], v[180:183], v[90:93]
	v_mfma_f32_16x16x32_bf16 v[78:81], v[228:231], v[188:191], v[78:81]
	v_mfma_f32_16x16x32_bf16 v[74:77], v[236:239], v[188:191], v[74:77]
	v_mfma_f32_16x16x32_bf16 v[70:73], v[228:231], v[196:199], v[70:73]
	v_mfma_f32_16x16x32_bf16 v[66:69], v[236:239], v[196:199], v[66:69]
	v_mfma_f32_16x16x32_bf16 v[110:113], v[232:235], v[176:179], v[110:113]
	v_mfma_f32_16x16x32_bf16 v[106:109], v[240:243], v[176:179], v[106:109]
	v_mfma_f32_16x16x32_bf16 v[94:97], v[232:235], v[184:187], v[94:97]
	v_mfma_f32_16x16x32_bf16 v[90:93], v[240:243], v[184:187], v[90:93]
	v_mfma_f32_16x16x32_bf16 v[78:81], v[232:235], v[192:195], v[78:81]
	v_mfma_f32_16x16x32_bf16 v[74:77], v[240:243], v[192:195], v[74:77]
	v_mfma_f32_16x16x32_bf16 v[70:73], v[232:235], v[224:227], v[70:73]
	v_mfma_f32_16x16x32_bf16 v[66:69], v[240:243], v[224:227], v[66:69]
	s_barrier
	s_mov_b32 m0, s54
	s_add_u32 s78, s50, s94
	s_addc_u32 s79, s51, s95
	ds_read_b128 v[172:175], v143 offset:16384
	ds_read_b128 v[176:179], v143 offset:17408
	ds_read_b128 v[180:183], v143 offset:18432
	ds_read_b128 v[184:187], v143 offset:19456
	ds_read_b128 v[188:191], v143 offset:20480
	ds_read_b128 v[192:195], v143 offset:21504
	ds_read_b128 v[196:199], v143 offset:22528
	ds_read_b128 v[224:227], v143 offset:23552
	global_load_lds_dwordx4 v130, s[50:51]
	s_mov_b32 m0, s55
	s_add_u32 s76, s48, s94
	s_addc_u32 s77, s49, s95
	global_load_lds_dwordx4 v132, s[50:51]
	s_mov_b32 m0, s64
	s_nop 0
	global_load_lds_dwordx4 v0, s[48:49]
	s_add_i32 m0, s64, 0x2000
	s_add_u32 s64, s48, 0x80000
	s_addc_u32 s65, s49, 0
	global_load_lds_dwordx4 v134, s[48:49]
	s_add_i32 s41, s41, s53
	s_mov_b32 m0, s41
	s_nop 0
	global_load_lds_dwordx4 v0, s[64:65]
	s_add_i32 m0, s41, 0x2000
	s_nop 0
	global_load_lds_dwordx4 v134, s[64:65]
	s_waitcnt vmcnt(6) lgkmcnt(0)
	s_barrier
	v_mfma_f32_16x16x32_bf16 v[62:65], v[144:147], v[172:175], v[62:65]
	v_mfma_f32_16x16x32_bf16 v[58:61], v[152:155], v[172:175], v[58:61]
	v_mfma_f32_16x16x32_bf16 v[54:57], v[144:147], v[180:183], v[54:57]
	v_mfma_f32_16x16x32_bf16 v[50:53], v[152:155], v[180:183], v[50:53]
	v_mfma_f32_16x16x32_bf16 v[38:41], v[144:147], v[188:191], v[38:41]
	v_mfma_f32_16x16x32_bf16 v[34:37], v[152:155], v[188:191], v[34:37]
	v_mfma_f32_16x16x32_bf16 v[22:25], v[144:147], v[196:199], v[22:25]
	v_mfma_f32_16x16x32_bf16 v[18:21], v[152:155], v[196:199], v[18:21]
	v_mfma_f32_16x16x32_bf16 v[62:65], v[148:151], v[176:179], v[62:65]
	v_mfma_f32_16x16x32_bf16 v[58:61], v[168:171], v[176:179], v[58:61]
	v_mfma_f32_16x16x32_bf16 v[54:57], v[148:151], v[184:187], v[54:57]
	v_mfma_f32_16x16x32_bf16 v[50:53], v[168:171], v[184:187], v[50:53]
	v_mfma_f32_16x16x32_bf16 v[38:41], v[148:151], v[192:195], v[38:41]
	v_mfma_f32_16x16x32_bf16 v[34:37], v[168:171], v[192:195], v[34:37]
	v_mfma_f32_16x16x32_bf16 v[22:25], v[148:151], v[224:227], v[22:25]
	v_mfma_f32_16x16x32_bf16 v[18:21], v[168:171], v[224:227], v[18:21]
	v_mfma_f32_16x16x32_bf16 v[46:49], v[228:231], v[172:175], v[46:49]
	v_mfma_f32_16x16x32_bf16 v[42:45], v[236:239], v[172:175], v[42:45]
	v_mfma_f32_16x16x32_bf16 v[30:33], v[228:231], v[180:183], v[30:33]
	v_mfma_f32_16x16x32_bf16 v[26:29], v[236:239], v[180:183], v[26:29]
	v_mfma_f32_16x16x32_bf16 v[14:17], v[228:231], v[188:191], v[14:17]
	v_mfma_f32_16x16x32_bf16 v[10:13], v[236:239], v[188:191], v[10:13]
	v_mfma_f32_16x16x32_bf16 v[6:9], v[228:231], v[196:199], v[6:9]
	v_mfma_f32_16x16x32_bf16 v[2:5], v[236:239], v[196:199], v[2:5]
	v_mfma_f32_16x16x32_bf16 v[46:49], v[232:235], v[176:179], v[46:49]
	v_mfma_f32_16x16x32_bf16 v[42:45], v[240:243], v[176:179], v[42:45]
	v_mfma_f32_16x16x32_bf16 v[30:33], v[232:235], v[184:187], v[30:33]
	v_mfma_f32_16x16x32_bf16 v[26:29], v[240:243], v[184:187], v[26:29]
	v_mfma_f32_16x16x32_bf16 v[14:17], v[232:235], v[192:195], v[14:17]
	v_mfma_f32_16x16x32_bf16 v[10:13], v[240:243], v[192:195], v[10:13]
	v_mfma_f32_16x16x32_bf16 v[6:9], v[232:235], v[224:227], v[6:9]
	v_mfma_f32_16x16x32_bf16 v[2:5], v[240:243], v[224:227], v[2:5]
	s_barrier
	s_add_i32 s41, 0, 0x18000
	ds_read_b128 v[144:147], v141 offset:32768
	ds_read_b128 v[148:151], v141 offset:33792
	ds_read_b128 v[152:155], v141 offset:34816
	ds_read_b128 v[168:171], v141 offset:35840
	s_add_u32 s50, s50, 0x80000
	s_addc_u32 s51, s51, 0
	ds_read_b128 v[172:175], v143 offset:32768
	ds_read_b128 v[176:179], v143 offset:33792
	ds_read_b128 v[180:183], v143 offset:34816
	ds_read_b128 v[184:187], v143 offset:35840
	ds_read_b128 v[188:191], v143 offset:36864
	ds_read_b128 v[192:195], v143 offset:37888
	ds_read_b128 v[196:199], v143 offset:38912
	ds_read_b128 v[224:227], v143 offset:39936
	s_mov_b32 m0, s56
	s_nop 0
	global_load_lds_dwordx4 v130, s[50:51]
	s_mov_b32 m0, s57
	s_nop 0
	global_load_lds_dwordx4 v132, s[50:51]
	s_add_i32 s50, 0, 0x1c000
	s_add_i32 s41, s41, s53
	ds_read_b128 v[228:231], v141 offset:49152
	ds_read_b128 v[232:235], v141 offset:50176
	ds_read_b128 v[236:239], v141 offset:51200
	ds_read_b128 v[240:243], v141 offset:52224
	s_waitcnt lgkmcnt(0)
	s_barrier
	v_mfma_f32_16x16x32_bf16 v[126:129], v[144:147], v[172:175], v[126:129]
	v_mfma_f32_16x16x32_bf16 v[122:125], v[152:155], v[172:175], v[122:125]
	v_mfma_f32_16x16x32_bf16 v[118:121], v[144:147], v[180:183], v[118:121]
	v_mfma_f32_16x16x32_bf16 v[114:117], v[152:155], v[180:183], v[114:117]
	v_mfma_f32_16x16x32_bf16 v[102:105], v[144:147], v[188:191], v[102:105]
	v_mfma_f32_16x16x32_bf16 v[98:101], v[152:155], v[188:191], v[98:101]
	v_mfma_f32_16x16x32_bf16 v[86:89], v[144:147], v[196:199], v[86:89]
	v_mfma_f32_16x16x32_bf16 v[82:85], v[152:155], v[196:199], v[82:85]
	v_mfma_f32_16x16x32_bf16 v[126:129], v[148:151], v[176:179], v[126:129]
	v_mfma_f32_16x16x32_bf16 v[122:125], v[168:171], v[176:179], v[122:125]
	v_mfma_f32_16x16x32_bf16 v[118:121], v[148:151], v[184:187], v[118:121]
	v_mfma_f32_16x16x32_bf16 v[114:117], v[168:171], v[184:187], v[114:117]
	v_mfma_f32_16x16x32_bf16 v[102:105], v[148:151], v[192:195], v[102:105]
	v_mfma_f32_16x16x32_bf16 v[98:101], v[168:171], v[192:195], v[98:101]
	v_mfma_f32_16x16x32_bf16 v[86:89], v[148:151], v[224:227], v[86:89]
	v_mfma_f32_16x16x32_bf16 v[82:85], v[168:171], v[224:227], v[82:85]
	v_mfma_f32_16x16x32_bf16 v[110:113], v[228:231], v[172:175], v[110:113]
	v_mfma_f32_16x16x32_bf16 v[106:109], v[236:239], v[172:175], v[106:109]
	v_mfma_f32_16x16x32_bf16 v[94:97], v[228:231], v[180:183], v[94:97]
	v_mfma_f32_16x16x32_bf16 v[90:93], v[236:239], v[180:183], v[90:93]
	v_mfma_f32_16x16x32_bf16 v[78:81], v[228:231], v[188:191], v[78:81]
	v_mfma_f32_16x16x32_bf16 v[74:77], v[236:239], v[188:191], v[74:77]
	v_mfma_f32_16x16x32_bf16 v[70:73], v[228:231], v[196:199], v[70:73]
	v_mfma_f32_16x16x32_bf16 v[66:69], v[236:239], v[196:199], v[66:69]
	v_mfma_f32_16x16x32_bf16 v[110:113], v[232:235], v[176:179], v[110:113]
	v_mfma_f32_16x16x32_bf16 v[106:109], v[240:243], v[176:179], v[106:109]
	v_mfma_f32_16x16x32_bf16 v[94:97], v[232:235], v[184:187], v[94:97]
	v_mfma_f32_16x16x32_bf16 v[90:93], v[240:243], v[184:187], v[90:93]
	v_mfma_f32_16x16x32_bf16 v[78:81], v[232:235], v[192:195], v[78:81]
	v_mfma_f32_16x16x32_bf16 v[74:77], v[240:243], v[192:195], v[74:77]
	v_mfma_f32_16x16x32_bf16 v[70:73], v[232:235], v[224:227], v[70:73]
	v_mfma_f32_16x16x32_bf16 v[66:69], v[240:243], v[224:227], v[66:69]
	s_barrier
	s_mov_b32 m0, s59
	ds_read_b128 v[172:175], v143 offset:49152
	ds_read_b128 v[176:179], v143 offset:50176
	ds_read_b128 v[180:183], v143 offset:51200
	ds_read_b128 v[184:187], v143 offset:52224
	ds_read_b128 v[188:191], v143 offset:53248
	ds_read_b128 v[192:195], v143 offset:54272
	ds_read_b128 v[196:199], v143 offset:55296
	ds_read_b128 v[224:227], v143 offset:56320
	global_load_lds_dwordx4 v130, s[78:79]
	s_mov_b32 m0, s60
	s_nop 0
	global_load_lds_dwordx4 v132, s[78:79]
	s_mov_b32 m0, s41
	s_nop 0
	global_load_lds_dwordx4 v0, s[76:77]
	s_add_i32 m0, s41, 0x2000
	s_add_u32 s48, s48, 0x80080
	s_addc_u32 s49, s49, 0
	global_load_lds_dwordx4 v134, s[76:77]
	s_add_i32 s41, s50, s53
	s_mov_b32 m0, s41
	s_nop 0
	global_load_lds_dwordx4 v0, s[48:49]
	s_add_i32 m0, s41, 0x2000
	s_nop 0
	global_load_lds_dwordx4 v134, s[48:49]
	s_waitcnt vmcnt(6) lgkmcnt(0)
	s_barrier
	v_mfma_f32_16x16x32_bf16 v[62:65], v[144:147], v[172:175], v[62:65]
	v_mfma_f32_16x16x32_bf16 v[58:61], v[152:155], v[172:175], v[58:61]
	v_mfma_f32_16x16x32_bf16 v[54:57], v[144:147], v[180:183], v[54:57]
	v_mfma_f32_16x16x32_bf16 v[50:53], v[152:155], v[180:183], v[50:53]
	v_mfma_f32_16x16x32_bf16 v[38:41], v[144:147], v[188:191], v[38:41]
	v_mfma_f32_16x16x32_bf16 v[34:37], v[152:155], v[188:191], v[34:37]
	v_mfma_f32_16x16x32_bf16 v[22:25], v[144:147], v[196:199], v[22:25]
	v_mfma_f32_16x16x32_bf16 v[18:21], v[152:155], v[196:199], v[18:21]
	v_mfma_f32_16x16x32_bf16 v[62:65], v[148:151], v[176:179], v[62:65]
	v_mfma_f32_16x16x32_bf16 v[58:61], v[168:171], v[176:179], v[58:61]
	v_mfma_f32_16x16x32_bf16 v[54:57], v[148:151], v[184:187], v[54:57]
	v_mfma_f32_16x16x32_bf16 v[50:53], v[168:171], v[184:187], v[50:53]
	v_mfma_f32_16x16x32_bf16 v[38:41], v[148:151], v[192:195], v[38:41]
	v_mfma_f32_16x16x32_bf16 v[34:37], v[168:171], v[192:195], v[34:37]
	v_mfma_f32_16x16x32_bf16 v[22:25], v[148:151], v[224:227], v[22:25]
	v_mfma_f32_16x16x32_bf16 v[18:21], v[168:171], v[224:227], v[18:21]
	v_mfma_f32_16x16x32_bf16 v[46:49], v[228:231], v[172:175], v[46:49]
	v_mfma_f32_16x16x32_bf16 v[42:45], v[236:239], v[172:175], v[42:45]
	v_mfma_f32_16x16x32_bf16 v[30:33], v[228:231], v[180:183], v[30:33]
	v_mfma_f32_16x16x32_bf16 v[26:29], v[236:239], v[180:183], v[26:29]
	v_mfma_f32_16x16x32_bf16 v[14:17], v[228:231], v[188:191], v[14:17]
	v_mfma_f32_16x16x32_bf16 v[10:13], v[236:239], v[188:191], v[10:13]
	v_mfma_f32_16x16x32_bf16 v[6:9], v[228:231], v[196:199], v[6:9]
	v_mfma_f32_16x16x32_bf16 v[2:5], v[236:239], v[196:199], v[2:5]
	v_mfma_f32_16x16x32_bf16 v[46:49], v[232:235], v[176:179], v[46:49]
	v_mfma_f32_16x16x32_bf16 v[42:45], v[240:243], v[176:179], v[42:45]
	v_mfma_f32_16x16x32_bf16 v[30:33], v[232:235], v[184:187], v[30:33]
	v_mfma_f32_16x16x32_bf16 v[26:29], v[240:243], v[184:187], v[26:29]
	v_mfma_f32_16x16x32_bf16 v[14:17], v[232:235], v[192:195], v[14:17]
	v_mfma_f32_16x16x32_bf16 v[10:13], v[240:243], v[192:195], v[10:13]
	v_mfma_f32_16x16x32_bf16 v[6:9], v[232:235], v[224:227], v[6:9]
	v_mfma_f32_16x16x32_bf16 v[2:5], v[240:243], v[224:227], v[2:5]
	s_barrier
	s_add_i32 s39, s39, 2
	s_add_u32 s46, s46, 0x100
	s_addc_u32 s47, s47, 0
	s_add_u32 s12, s12, 0x100
	s_addc_u32 s13, s13, 0
	s_cmp_gt_u32 s39, 29
	s_cbranch_scc0 .LBB0_572
	s_cmp_lg_u32 s62, 0
	s_cbranch_scc0 .LBB0_575
	s_lshl_b32 s39, s61, 8
	s_mov_b64 s[12:13], 0
	s_branch .LBB0_576

.LBB0_788:
	s_add_u32 s39, s46, 0xfff80080
	s_addc_u32 s48, s47, -1
	s_add_i32 s64, 0, 0x10000
	ds_read_b128 v[144:147], v141
	ds_read_b128 v[148:151], v141 offset:1024
	ds_read_b128 v[152:155], v141 offset:2048
	ds_read_b128 v[168:171], v141 offset:3072
	s_cmp_eq_u32 s13, 28
	s_cselect_b32 s51, s43, s48
	s_cselect_b32 s50, s42, s39
	s_cselect_b32 s49, s45, s12
	s_cselect_b32 s48, s44, s1
	ds_read_b128 v[172:175], v143
	ds_read_b128 v[176:179], v143 offset:1024
	ds_read_b128 v[180:183], v143 offset:2048
	ds_read_b128 v[184:187], v143 offset:3072
	ds_read_b128 v[188:191], v143 offset:4096
	ds_read_b128 v[192:195], v143 offset:5120
	ds_read_b128 v[196:199], v143 offset:6144
	ds_read_b128 v[224:227], v143 offset:7168
	s_add_i32 m0, s54, 0xc000
	s_nop 0
	global_load_lds_dwordx4 v136, s[46:47]
	s_add_i32 m0, s54, 0xe000
	s_add_i32 s39, 0, 0x14000
	global_load_lds_dwordx4 v138, s[46:47]
	s_add_i32 s64, s64, s53
	ds_read_b128 v[228:231], v141 offset:16384
	ds_read_b128 v[232:235], v141 offset:17408
	ds_read_b128 v[236:239], v141 offset:18432
	ds_read_b128 v[240:243], v141 offset:19456
	s_waitcnt lgkmcnt(0)
	s_barrier
	v_mfma_f32_16x16x32_bf16 v[126:129], v[144:147], v[172:175], v[126:129]
	v_mfma_f32_16x16x32_bf16 v[122:125], v[152:155], v[172:175], v[122:125]
	v_mfma_f32_16x16x32_bf16 v[118:121], v[144:147], v[180:183], v[118:121]
	v_mfma_f32_16x16x32_bf16 v[114:117], v[152:155], v[180:183], v[114:117]
	v_mfma_f32_16x16x32_bf16 v[102:105], v[144:147], v[188:191], v[102:105]
	v_mfma_f32_16x16x32_bf16 v[98:101], v[152:155], v[188:191], v[98:101]
	v_mfma_f32_16x16x32_bf16 v[86:89], v[144:147], v[196:199], v[86:89]
	v_mfma_f32_16x16x32_bf16 v[82:85], v[152:155], v[196:199], v[82:85]
	v_mfma_f32_16x16x32_bf16 v[126:129], v[148:151], v[176:179], v[126:129]
	v_mfma_f32_16x16x32_bf16 v[122:125], v[168:171], v[176:179], v[122:125]
	v_mfma_f32_16x16x32_bf16 v[118:121], v[148:151], v[184:187], v[118:121]
	v_mfma_f32_16x16x32_bf16 v[114:117], v[168:171], v[184:187], v[114:117]
	v_mfma_f32_16x16x32_bf16 v[102:105], v[148:151], v[192:195], v[102:105]
	v_mfma_f32_16x16x32_bf16 v[98:101], v[168:171], v[192:195], v[98:101]
	v_mfma_f32_16x16x32_bf16 v[86:89], v[148:151], v[224:227], v[86:89]
	v_mfma_f32_16x16x32_bf16 v[82:85], v[168:171], v[224:227], v[82:85]
	v_mfma_f32_16x16x32_bf16 v[110:113], v[228:231], v[172:175], v[110:113]
	v_mfma_f32_16x16x32_bf16 v[106:109], v[236:239], v[172:175], v[106:109]
	v_mfma_f32_16x16x32_bf16 v[94:97], v[228:231], v[180:183], v[94:97]
	v_mfma_f32_16x16x32_bf16 v[90:93], v[236:239], v[180:183], v[90:93]
	v_mfma_f32_16x16x32_bf16 v[78:81], v[228:231], v[188:191], v[78:81]
	v_mfma_f32_16x16x32_bf16 v[74:77], v[236:239], v[188:191], v[74:77]
	v_mfma_f32_16x16x32_bf16 v[70:73], v[228:231], v[196:199], v[70:73]
	v_mfma_f32_16x16x32_bf16 v[66:69], v[236:239], v[196:199], v[66:69]
	v_mfma_f32_16x16x32_bf16 v[110:113], v[232:235], v[176:179], v[110:113]
	v_mfma_f32_16x16x32_bf16 v[106:109], v[240:243], v[176:179], v[106:109]
	v_mfma_f32_16x16x32_bf16 v[94:97], v[232:235], v[184:187], v[94:97]
	v_mfma_f32_16x16x32_bf16 v[90:93], v[240:243], v[184:187], v[90:93]
	v_mfma_f32_16x16x32_bf16 v[78:81], v[232:235], v[192:195], v[78:81]
	v_mfma_f32_16x16x32_bf16 v[74:77], v[240:243], v[192:195], v[74:77]
	v_mfma_f32_16x16x32_bf16 v[70:73], v[232:235], v[224:227], v[70:73]
	v_mfma_f32_16x16x32_bf16 v[66:69], v[240:243], v[224:227], v[66:69]
	s_barrier
	s_mov_b32 m0, s54
	s_add_u32 s78, s50, s94
	s_addc_u32 s79, s51, s95
	ds_read_b128 v[172:175], v143 offset:16384
	ds_read_b128 v[176:179], v143 offset:17408
	ds_read_b128 v[180:183], v143 offset:18432
	ds_read_b128 v[184:187], v143 offset:19456
	ds_read_b128 v[188:191], v143 offset:20480
	ds_read_b128 v[192:195], v143 offset:21504
	ds_read_b128 v[196:199], v143 offset:22528
	ds_read_b128 v[224:227], v143 offset:23552
	global_load_lds_dwordx4 v130, s[50:51]
	s_mov_b32 m0, s55
	s_add_u32 s76, s48, s94
	s_addc_u32 s77, s49, s95
	global_load_lds_dwordx4 v132, s[50:51]
	s_mov_b32 m0, s64
	s_nop 0
	global_load_lds_dwordx4 v0, s[48:49]
	s_add_i32 m0, s64, 0x2000
	s_add_u32 s64, s48, 0x80000
	s_addc_u32 s65, s49, 0
	global_load_lds_dwordx4 v134, s[48:49]
	s_add_i32 s39, s39, s53
	s_mov_b32 m0, s39
	s_nop 0
	global_load_lds_dwordx4 v0, s[64:65]
	s_add_i32 m0, s39, 0x2000
	s_nop 0
	global_load_lds_dwordx4 v134, s[64:65]
	s_waitcnt vmcnt(6) lgkmcnt(0)
	s_barrier
	v_mfma_f32_16x16x32_bf16 v[62:65], v[144:147], v[172:175], v[62:65]
	v_mfma_f32_16x16x32_bf16 v[58:61], v[152:155], v[172:175], v[58:61]
	v_mfma_f32_16x16x32_bf16 v[54:57], v[144:147], v[180:183], v[54:57]
	v_mfma_f32_16x16x32_bf16 v[50:53], v[152:155], v[180:183], v[50:53]
	v_mfma_f32_16x16x32_bf16 v[38:41], v[144:147], v[188:191], v[38:41]
	v_mfma_f32_16x16x32_bf16 v[34:37], v[152:155], v[188:191], v[34:37]
	v_mfma_f32_16x16x32_bf16 v[22:25], v[144:147], v[196:199], v[22:25]
	v_mfma_f32_16x16x32_bf16 v[18:21], v[152:155], v[196:199], v[18:21]
	v_mfma_f32_16x16x32_bf16 v[62:65], v[148:151], v[176:179], v[62:65]
	v_mfma_f32_16x16x32_bf16 v[58:61], v[168:171], v[176:179], v[58:61]
	v_mfma_f32_16x16x32_bf16 v[54:57], v[148:151], v[184:187], v[54:57]
	v_mfma_f32_16x16x32_bf16 v[50:53], v[168:171], v[184:187], v[50:53]
	v_mfma_f32_16x16x32_bf16 v[38:41], v[148:151], v[192:195], v[38:41]
	v_mfma_f32_16x16x32_bf16 v[34:37], v[168:171], v[192:195], v[34:37]
	v_mfma_f32_16x16x32_bf16 v[22:25], v[148:151], v[224:227], v[22:25]
	v_mfma_f32_16x16x32_bf16 v[18:21], v[168:171], v[224:227], v[18:21]
	v_mfma_f32_16x16x32_bf16 v[46:49], v[228:231], v[172:175], v[46:49]
	v_mfma_f32_16x16x32_bf16 v[42:45], v[236:239], v[172:175], v[42:45]
	v_mfma_f32_16x16x32_bf16 v[30:33], v[228:231], v[180:183], v[30:33]
	v_mfma_f32_16x16x32_bf16 v[26:29], v[236:239], v[180:183], v[26:29]
	v_mfma_f32_16x16x32_bf16 v[14:17], v[228:231], v[188:191], v[14:17]
	v_mfma_f32_16x16x32_bf16 v[10:13], v[236:239], v[188:191], v[10:13]
	v_mfma_f32_16x16x32_bf16 v[6:9], v[228:231], v[196:199], v[6:9]
	v_mfma_f32_16x16x32_bf16 v[2:5], v[236:239], v[196:199], v[2:5]
	v_mfma_f32_16x16x32_bf16 v[46:49], v[232:235], v[176:179], v[46:49]
	v_mfma_f32_16x16x32_bf16 v[42:45], v[240:243], v[176:179], v[42:45]
	v_mfma_f32_16x16x32_bf16 v[30:33], v[232:235], v[184:187], v[30:33]
	v_mfma_f32_16x16x32_bf16 v[26:29], v[240:243], v[184:187], v[26:29]
	v_mfma_f32_16x16x32_bf16 v[14:17], v[232:235], v[192:195], v[14:17]
	v_mfma_f32_16x16x32_bf16 v[10:13], v[240:243], v[192:195], v[10:13]
	v_mfma_f32_16x16x32_bf16 v[6:9], v[232:235], v[224:227], v[6:9]
	v_mfma_f32_16x16x32_bf16 v[2:5], v[240:243], v[224:227], v[2:5]
	s_barrier
	s_add_i32 s39, 0, 0x18000
	ds_read_b128 v[144:147], v141 offset:32768
	ds_read_b128 v[148:151], v141 offset:33792
	ds_read_b128 v[152:155], v141 offset:34816
	ds_read_b128 v[168:171], v141 offset:35840
	s_add_u32 s50, s50, 0x80000
	s_addc_u32 s51, s51, 0
	ds_read_b128 v[172:175], v143 offset:32768
	ds_read_b128 v[176:179], v143 offset:33792
	ds_read_b128 v[180:183], v143 offset:34816
	ds_read_b128 v[184:187], v143 offset:35840
	ds_read_b128 v[188:191], v143 offset:36864
	ds_read_b128 v[192:195], v143 offset:37888
	ds_read_b128 v[196:199], v143 offset:38912
	ds_read_b128 v[224:227], v143 offset:39936
	s_mov_b32 m0, s56
	s_nop 0
	global_load_lds_dwordx4 v130, s[50:51]
	s_mov_b32 m0, s57
	s_nop 0
	global_load_lds_dwordx4 v132, s[50:51]
	s_add_i32 s50, 0, 0x1c000
	s_add_i32 s39, s39, s53
	ds_read_b128 v[228:231], v141 offset:49152
	ds_read_b128 v[232:235], v141 offset:50176
	ds_read_b128 v[236:239], v141 offset:51200
	ds_read_b128 v[240:243], v141 offset:52224
	s_waitcnt lgkmcnt(0)
	s_barrier
	v_mfma_f32_16x16x32_bf16 v[126:129], v[144:147], v[172:175], v[126:129]
	v_mfma_f32_16x16x32_bf16 v[122:125], v[152:155], v[172:175], v[122:125]
	v_mfma_f32_16x16x32_bf16 v[118:121], v[144:147], v[180:183], v[118:121]
	v_mfma_f32_16x16x32_bf16 v[114:117], v[152:155], v[180:183], v[114:117]
	v_mfma_f32_16x16x32_bf16 v[102:105], v[144:147], v[188:191], v[102:105]
	v_mfma_f32_16x16x32_bf16 v[98:101], v[152:155], v[188:191], v[98:101]
	v_mfma_f32_16x16x32_bf16 v[86:89], v[144:147], v[196:199], v[86:89]
	v_mfma_f32_16x16x32_bf16 v[82:85], v[152:155], v[196:199], v[82:85]
	v_mfma_f32_16x16x32_bf16 v[126:129], v[148:151], v[176:179], v[126:129]
	v_mfma_f32_16x16x32_bf16 v[122:125], v[168:171], v[176:179], v[122:125]
	v_mfma_f32_16x16x32_bf16 v[118:121], v[148:151], v[184:187], v[118:121]
	v_mfma_f32_16x16x32_bf16 v[114:117], v[168:171], v[184:187], v[114:117]
	v_mfma_f32_16x16x32_bf16 v[102:105], v[148:151], v[192:195], v[102:105]
	v_mfma_f32_16x16x32_bf16 v[98:101], v[168:171], v[192:195], v[98:101]
	v_mfma_f32_16x16x32_bf16 v[86:89], v[148:151], v[224:227], v[86:89]
	v_mfma_f32_16x16x32_bf16 v[82:85], v[168:171], v[224:227], v[82:85]
	v_mfma_f32_16x16x32_bf16 v[110:113], v[228:231], v[172:175], v[110:113]
	v_mfma_f32_16x16x32_bf16 v[106:109], v[236:239], v[172:175], v[106:109]
	v_mfma_f32_16x16x32_bf16 v[94:97], v[228:231], v[180:183], v[94:97]
	v_mfma_f32_16x16x32_bf16 v[90:93], v[236:239], v[180:183], v[90:93]
	v_mfma_f32_16x16x32_bf16 v[78:81], v[228:231], v[188:191], v[78:81]
	v_mfma_f32_16x16x32_bf16 v[74:77], v[236:239], v[188:191], v[74:77]
	v_mfma_f32_16x16x32_bf16 v[70:73], v[228:231], v[196:199], v[70:73]
	v_mfma_f32_16x16x32_bf16 v[66:69], v[236:239], v[196:199], v[66:69]
	v_mfma_f32_16x16x32_bf16 v[110:113], v[232:235], v[176:179], v[110:113]
	v_mfma_f32_16x16x32_bf16 v[106:109], v[240:243], v[176:179], v[106:109]
	v_mfma_f32_16x16x32_bf16 v[94:97], v[232:235], v[184:187], v[94:97]
	v_mfma_f32_16x16x32_bf16 v[90:93], v[240:243], v[184:187], v[90:93]
	v_mfma_f32_16x16x32_bf16 v[78:81], v[232:235], v[192:195], v[78:81]
	v_mfma_f32_16x16x32_bf16 v[74:77], v[240:243], v[192:195], v[74:77]
	v_mfma_f32_16x16x32_bf16 v[70:73], v[232:235], v[224:227], v[70:73]
	v_mfma_f32_16x16x32_bf16 v[66:69], v[240:243], v[224:227], v[66:69]
	s_barrier
	s_mov_b32 m0, s59
	ds_read_b128 v[172:175], v143 offset:49152
	ds_read_b128 v[176:179], v143 offset:50176
	ds_read_b128 v[180:183], v143 offset:51200
	ds_read_b128 v[184:187], v143 offset:52224
	ds_read_b128 v[188:191], v143 offset:53248
	ds_read_b128 v[192:195], v143 offset:54272
	ds_read_b128 v[196:199], v143 offset:55296
	ds_read_b128 v[224:227], v143 offset:56320
	global_load_lds_dwordx4 v130, s[78:79]
	s_mov_b32 m0, s61
	s_nop 0
	global_load_lds_dwordx4 v132, s[78:79]
	s_mov_b32 m0, s39
	s_nop 0
	global_load_lds_dwordx4 v0, s[76:77]
	s_add_i32 m0, s39, 0x2000
	s_add_u32 s48, s48, 0x80080
	s_addc_u32 s49, s49, 0
	global_load_lds_dwordx4 v134, s[76:77]
	s_add_i32 s39, s50, s53
	s_mov_b32 m0, s39
	s_nop 0
	global_load_lds_dwordx4 v0, s[48:49]
	s_add_i32 m0, s39, 0x2000
	s_nop 0
	global_load_lds_dwordx4 v134, s[48:49]
	s_waitcnt vmcnt(6) lgkmcnt(0)
	s_barrier
	v_mfma_f32_16x16x32_bf16 v[62:65], v[144:147], v[172:175], v[62:65]
	v_mfma_f32_16x16x32_bf16 v[58:61], v[152:155], v[172:175], v[58:61]
	v_mfma_f32_16x16x32_bf16 v[54:57], v[144:147], v[180:183], v[54:57]
	v_mfma_f32_16x16x32_bf16 v[50:53], v[152:155], v[180:183], v[50:53]
	v_mfma_f32_16x16x32_bf16 v[38:41], v[144:147], v[188:191], v[38:41]
	v_mfma_f32_16x16x32_bf16 v[34:37], v[152:155], v[188:191], v[34:37]
	v_mfma_f32_16x16x32_bf16 v[22:25], v[144:147], v[196:199], v[22:25]
	v_mfma_f32_16x16x32_bf16 v[18:21], v[152:155], v[196:199], v[18:21]
	v_mfma_f32_16x16x32_bf16 v[62:65], v[148:151], v[176:179], v[62:65]
	v_mfma_f32_16x16x32_bf16 v[58:61], v[168:171], v[176:179], v[58:61]
	v_mfma_f32_16x16x32_bf16 v[54:57], v[148:151], v[184:187], v[54:57]
	v_mfma_f32_16x16x32_bf16 v[50:53], v[168:171], v[184:187], v[50:53]
	v_mfma_f32_16x16x32_bf16 v[38:41], v[148:151], v[192:195], v[38:41]
	v_mfma_f32_16x16x32_bf16 v[34:37], v[168:171], v[192:195], v[34:37]
	v_mfma_f32_16x16x32_bf16 v[22:25], v[148:151], v[224:227], v[22:25]
	v_mfma_f32_16x16x32_bf16 v[18:21], v[168:171], v[224:227], v[18:21]
	v_mfma_f32_16x16x32_bf16 v[46:49], v[228:231], v[172:175], v[46:49]
	v_mfma_f32_16x16x32_bf16 v[42:45], v[236:239], v[172:175], v[42:45]
	v_mfma_f32_16x16x32_bf16 v[30:33], v[228:231], v[180:183], v[30:33]
	v_mfma_f32_16x16x32_bf16 v[26:29], v[236:239], v[180:183], v[26:29]
	v_mfma_f32_16x16x32_bf16 v[14:17], v[228:231], v[188:191], v[14:17]
	v_mfma_f32_16x16x32_bf16 v[10:13], v[236:239], v[188:191], v[10:13]
	v_mfma_f32_16x16x32_bf16 v[6:9], v[228:231], v[196:199], v[6:9]
	v_mfma_f32_16x16x32_bf16 v[2:5], v[236:239], v[196:199], v[2:5]
	v_mfma_f32_16x16x32_bf16 v[46:49], v[232:235], v[176:179], v[46:49]
	v_mfma_f32_16x16x32_bf16 v[42:45], v[240:243], v[176:179], v[42:45]
	v_mfma_f32_16x16x32_bf16 v[30:33], v[232:235], v[184:187], v[30:33]
	v_mfma_f32_16x16x32_bf16 v[26:29], v[240:243], v[184:187], v[26:29]
	v_mfma_f32_16x16x32_bf16 v[14:17], v[232:235], v[192:195], v[14:17]
	v_mfma_f32_16x16x32_bf16 v[10:13], v[240:243], v[192:195], v[10:13]
	v_mfma_f32_16x16x32_bf16 v[6:9], v[232:235], v[224:227], v[6:9]
	v_mfma_f32_16x16x32_bf16 v[2:5], v[240:243], v[224:227], v[2:5]
	s_barrier
	s_add_i32 s13, s13, 2
	s_add_u32 s46, s46, 0x100
	s_addc_u32 s47, s47, 0
	s_add_u32 s1, s1, 0x100
	s_addc_u32 s12, s12, 0
	s_cmp_gt_u32 s13, 29
	s_cbranch_scc0 .LBB0_788
	s_cmp_lg_u32 s62, 0
	s_cbranch_scc0 .LBB0_791
	s_lshl_b32 s1, s60, 8
	s_mov_b64 s[12:13], 0
	s_branch .LBB0_792
